# v43 + GEMM K-loops: MFMA groups of 8 issued in snake order (one operand changes between consecutive MFMAs) to cut operand toggling
# baseline (speedup 1.0000x reference)
.LBB0_220:
	ds_read_b128 v[148:151], v173
	ds_read_b128 v[152:155], v173 offset:1024
	ds_read_b128 v[156:159], v173 offset:2048
	ds_read_b128 v[160:163], v173 offset:3072
	ds_read_b128 v[164:167], v174
	ds_read_b128 v[180:183], v174 offset:1024
	ds_read_b128 v[184:187], v174 offset:2048
	ds_read_b128 v[188:191], v174 offset:3072
	s_add_u32 s52, s50, 0xfffc0080
	s_addc_u32 s53, s51, -1
	s_cmp_eq_u32 s66, 12
	s_cselect_b32 s55, s9, s53
	s_cselect_b32 s54, s11, s52
	s_cselect_b32 s53, s20, s45
	s_cselect_b32 s52, s33, s43
	v_lshl_add_u64 v[168:169], s[50:51], 0, v[140:141]
	s_add_i32 m0, s35, 0xc000
	ds_read_b128 v[192:195], v175
	ds_read_b128 v[196:199], v175 offset:1024
	ds_read_b128 v[204:207], v175 offset:2048
	ds_read_b128 v[208:211], v175 offset:3072
	ds_read_b128 v[212:215], v175 offset:4096
	ds_read_b128 v[216:219], v175 offset:5120
	ds_read_b128 v[220:223], v175 offset:6144
	ds_read_b128 v[224:227], v175 offset:7168
	global_load_lds_dwordx4 v[168:169], off
	v_lshl_add_u64 v[168:169], s[50:51], 0, v[142:143]
	s_add_i32 m0, s35, 0xe000
	s_nop 0
	global_load_lds_dwordx4 v[168:169], off
	s_waitcnt vmcnt(8)
	s_waitcnt lgkmcnt(0)
	s_barrier
	s_setprio 1
	s_waitcnt lgkmcnt(0)
	v_mfma_f32_16x16x32_bf16 v[124:127], v[148:151], v[192:195], v[124:127]
	v_mfma_f32_16x16x32_bf16 v[120:123], v[156:159], v[192:195], v[120:123]
	v_mfma_f32_16x16x32_bf16 v[104:107], v[156:159], v[204:207], v[104:107]
	v_mfma_f32_16x16x32_bf16 v[108:111], v[148:151], v[204:207], v[108:111]
	v_mfma_f32_16x16x32_bf16 v[92:95], v[148:151], v[212:215], v[92:95]
	v_mfma_f32_16x16x32_bf16 v[88:91], v[156:159], v[212:215], v[88:91]
	v_mfma_f32_16x16x32_bf16 v[72:75], v[156:159], v[220:223], v[72:75]
	v_mfma_f32_16x16x32_bf16 v[76:79], v[148:151], v[220:223], v[76:79]
	v_mfma_f32_16x16x32_bf16 v[124:127], v[152:155], v[196:199], v[124:127]
	v_mfma_f32_16x16x32_bf16 v[120:123], v[160:163], v[196:199], v[120:123]
	v_mfma_f32_16x16x32_bf16 v[104:107], v[160:163], v[208:211], v[104:107]
	v_mfma_f32_16x16x32_bf16 v[108:111], v[152:155], v[208:211], v[108:111]
	v_mfma_f32_16x16x32_bf16 v[92:95], v[152:155], v[216:219], v[92:95]
	v_mfma_f32_16x16x32_bf16 v[88:91], v[160:163], v[216:219], v[88:91]
	v_mfma_f32_16x16x32_bf16 v[72:75], v[160:163], v[224:227], v[72:75]
	v_mfma_f32_16x16x32_bf16 v[76:79], v[152:155], v[224:227], v[76:79]
	s_setprio 0
	s_setprio 1
	v_mfma_f32_16x16x32_bf16 v[116:119], v[164:167], v[192:195], v[116:119]
	v_mfma_f32_16x16x32_bf16 v[112:115], v[184:187], v[192:195], v[112:115]
	v_mfma_f32_16x16x32_bf16 v[96:99], v[184:187], v[204:207], v[96:99]
	v_mfma_f32_16x16x32_bf16 v[100:103], v[164:167], v[204:207], v[100:103]
	v_mfma_f32_16x16x32_bf16 v[84:87], v[164:167], v[212:215], v[84:87]
	v_mfma_f32_16x16x32_bf16 v[80:83], v[184:187], v[212:215], v[80:83]
	v_mfma_f32_16x16x32_bf16 v[64:67], v[184:187], v[220:223], v[64:67]
	v_mfma_f32_16x16x32_bf16 v[68:71], v[164:167], v[220:223], v[68:71]
	v_mfma_f32_16x16x32_bf16 v[116:119], v[180:183], v[196:199], v[116:119]
	v_mfma_f32_16x16x32_bf16 v[112:115], v[188:191], v[196:199], v[112:115]
	v_mfma_f32_16x16x32_bf16 v[96:99], v[188:191], v[208:211], v[96:99]
	v_mfma_f32_16x16x32_bf16 v[100:103], v[180:183], v[208:211], v[100:103]
	v_mfma_f32_16x16x32_bf16 v[84:87], v[180:183], v[216:219], v[84:87]
	v_mfma_f32_16x16x32_bf16 v[80:83], v[188:191], v[216:219], v[80:83]
	v_mfma_f32_16x16x32_bf16 v[64:67], v[188:191], v[224:227], v[64:67]
	v_mfma_f32_16x16x32_bf16 v[68:71], v[180:183], v[224:227], v[68:71]
	s_setprio 0
	s_barrier
	s_add_i32 s67, s63, s31
	v_lshl_add_u64 v[168:169], s[52:53], 0, v[130:131]
	s_mov_b32 m0, s67
	ds_read_b128 v[192:195], v175 offset:16384
	ds_read_b128 v[196:199], v175 offset:17408
	ds_read_b128 v[204:207], v175 offset:18432
	ds_read_b128 v[208:211], v175 offset:19456
	ds_read_b128 v[212:215], v175 offset:20480
	ds_read_b128 v[216:219], v175 offset:21504
	ds_read_b128 v[220:223], v175 offset:22528
	ds_read_b128 v[224:227], v175 offset:23552
	global_load_lds_dwordx4 v[168:169], off
	s_add_i32 m0, s67, 0x2000
	s_add_u32 s68, s52, 0x40000
	v_lshl_add_u64 v[200:201], s[52:53], 0, v[134:135]
	s_addc_u32 s69, s53, 0
	s_add_i32 s67, s64, s31
	global_load_lds_dwordx4 v[200:201], off
	v_lshl_add_u64 v[228:229], s[68:69], 0, v[130:131]
	s_mov_b32 m0, s67
	v_lshl_add_u64 v[230:231], s[54:55], 0, v[132:133]
	global_load_lds_dwordx4 v[228:229], off
	v_lshl_add_u64 v[228:229], s[68:69], 0, v[134:135]
	s_add_i32 m0, s67, 0x2000
	s_nop 0
	global_load_lds_dwordx4 v[228:229], off
	v_lshl_add_u64 v[228:229], s[54:55], 0, v[128:129]
	s_mov_b32 m0, s35
	s_nop 0
	global_load_lds_dwordx4 v[228:229], off
	s_mov_b32 m0, s37
	s_nop 0
	global_load_lds_dwordx4 v[230:231], off
	s_waitcnt vmcnt(8)
	s_waitcnt lgkmcnt(0)
	s_barrier
	s_setprio 1
	s_waitcnt lgkmcnt(0)
	v_mfma_f32_16x16x32_bf16 v[60:63], v[148:151], v[192:195], v[60:63]
	v_mfma_f32_16x16x32_bf16 v[56:59], v[156:159], v[192:195], v[56:59]
	v_mfma_f32_16x16x32_bf16 v[40:43], v[156:159], v[204:207], v[40:43]
	v_mfma_f32_16x16x32_bf16 v[44:47], v[148:151], v[204:207], v[44:47]
	v_mfma_f32_16x16x32_bf16 v[28:31], v[148:151], v[212:215], v[28:31]
	v_mfma_f32_16x16x32_bf16 v[24:27], v[156:159], v[212:215], v[24:27]
	v_mfma_f32_16x16x32_bf16 v[8:11], v[156:159], v[220:223], v[8:11]
	v_mfma_f32_16x16x32_bf16 v[12:15], v[148:151], v[220:223], v[12:15]
	v_mfma_f32_16x16x32_bf16 v[60:63], v[152:155], v[196:199], v[60:63]
	v_mfma_f32_16x16x32_bf16 v[56:59], v[160:163], v[196:199], v[56:59]
	v_mfma_f32_16x16x32_bf16 v[40:43], v[160:163], v[208:211], v[40:43]
	v_mfma_f32_16x16x32_bf16 v[44:47], v[152:155], v[208:211], v[44:47]
	v_mfma_f32_16x16x32_bf16 v[28:31], v[152:155], v[216:219], v[28:31]
	v_mfma_f32_16x16x32_bf16 v[24:27], v[160:163], v[216:219], v[24:27]
	v_mfma_f32_16x16x32_bf16 v[8:11], v[160:163], v[224:227], v[8:11]
	v_mfma_f32_16x16x32_bf16 v[12:15], v[152:155], v[224:227], v[12:15]
	s_setprio 0
	s_setprio 1
	v_mfma_f32_16x16x32_bf16 v[52:55], v[164:167], v[192:195], v[52:55]
	v_mfma_f32_16x16x32_bf16 v[48:51], v[184:187], v[192:195], v[48:51]
	v_mfma_f32_16x16x32_bf16 v[32:35], v[184:187], v[204:207], v[32:35]
	v_mfma_f32_16x16x32_bf16 v[36:39], v[164:167], v[204:207], v[36:39]
	v_mfma_f32_16x16x32_bf16 v[20:23], v[164:167], v[212:215], v[20:23]
	v_mfma_f32_16x16x32_bf16 v[16:19], v[184:187], v[212:215], v[16:19]
	v_mfma_f32_16x16x32_bf16 v[0:3], v[184:187], v[220:223], v[0:3]
	v_mfma_f32_16x16x32_bf16 v[4:7], v[164:167], v[220:223], v[4:7]
	v_mfma_f32_16x16x32_bf16 v[52:55], v[180:183], v[196:199], v[52:55]
	v_mfma_f32_16x16x32_bf16 v[48:51], v[188:191], v[196:199], v[48:51]
	v_mfma_f32_16x16x32_bf16 v[32:35], v[188:191], v[208:211], v[32:35]
	v_mfma_f32_16x16x32_bf16 v[36:39], v[180:183], v[208:211], v[36:39]
	v_mfma_f32_16x16x32_bf16 v[20:23], v[180:183], v[216:219], v[20:23]
	v_mfma_f32_16x16x32_bf16 v[16:19], v[188:191], v[216:219], v[16:19]
	v_mfma_f32_16x16x32_bf16 v[0:3], v[188:191], v[224:227], v[0:3]
	v_mfma_f32_16x16x32_bf16 v[4:7], v[180:183], v[224:227], v[4:7]
	s_setprio 0
	s_barrier
	s_add_i32 s67, 0, 0x18000
	v_add_u32_e32 v137, s67, v171
	s_add_i32 s68, 0, 0x1c000
	ds_read_b128 v[148:151], v137
	ds_read_b128 v[152:155], v137 offset:1024
	ds_read_b128 v[156:159], v137 offset:2048
	ds_read_b128 v[160:163], v137 offset:3072
	v_add_u32_e32 v137, s68, v171
	ds_read_b128 v[164:167], v137
	ds_read_b128 v[180:183], v137 offset:1024
	ds_read_b128 v[184:187], v137 offset:2048
	ds_read_b128 v[188:191], v137 offset:3072
	s_add_u32 s54, s54, 0x40000
	s_addc_u32 s55, s55, 0
	s_mov_b32 m0, s39
	v_lshl_add_u64 v[232:233], s[54:55], 0, v[128:129]
	ds_read_b128 v[192:195], v175 offset:32768
	ds_read_b128 v[196:199], v175 offset:33792
	ds_read_b128 v[204:207], v175 offset:34816
	ds_read_b128 v[208:211], v175 offset:35840
	ds_read_b128 v[212:215], v175 offset:36864
	ds_read_b128 v[216:219], v175 offset:37888
	ds_read_b128 v[220:223], v175 offset:38912
	ds_read_b128 v[224:227], v175 offset:39936
	global_load_lds_dwordx4 v[232:233], off
	v_lshl_add_u64 v[232:233], s[54:55], 0, v[132:133]
	s_mov_b32 m0, s41
	s_nop 0
	global_load_lds_dwordx4 v[232:233], off
	s_waitcnt vmcnt(8)
	s_waitcnt lgkmcnt(0)
	s_barrier
	s_setprio 1
	s_waitcnt lgkmcnt(0)
	v_mfma_f32_16x16x32_bf16 v[124:127], v[148:151], v[192:195], v[124:127]
	v_mfma_f32_16x16x32_bf16 v[120:123], v[156:159], v[192:195], v[120:123]
	v_mfma_f32_16x16x32_bf16 v[104:107], v[156:159], v[204:207], v[104:107]
	v_mfma_f32_16x16x32_bf16 v[108:111], v[148:151], v[204:207], v[108:111]
	v_mfma_f32_16x16x32_bf16 v[92:95], v[148:151], v[212:215], v[92:95]
	v_mfma_f32_16x16x32_bf16 v[88:91], v[156:159], v[212:215], v[88:91]
	v_mfma_f32_16x16x32_bf16 v[72:75], v[156:159], v[220:223], v[72:75]
	v_mfma_f32_16x16x32_bf16 v[76:79], v[148:151], v[220:223], v[76:79]
	v_mfma_f32_16x16x32_bf16 v[124:127], v[152:155], v[196:199], v[124:127]
	v_mfma_f32_16x16x32_bf16 v[120:123], v[160:163], v[196:199], v[120:123]
	v_mfma_f32_16x16x32_bf16 v[104:107], v[160:163], v[208:211], v[104:107]
	v_mfma_f32_16x16x32_bf16 v[108:111], v[152:155], v[208:211], v[108:111]
	v_mfma_f32_16x16x32_bf16 v[92:95], v[152:155], v[216:219], v[92:95]
	v_mfma_f32_16x16x32_bf16 v[88:91], v[160:163], v[216:219], v[88:91]
	v_mfma_f32_16x16x32_bf16 v[72:75], v[160:163], v[224:227], v[72:75]
	v_mfma_f32_16x16x32_bf16 v[76:79], v[152:155], v[224:227], v[76:79]
	s_setprio 0
	s_setprio 1
	v_mfma_f32_16x16x32_bf16 v[116:119], v[164:167], v[192:195], v[116:119]
	v_mfma_f32_16x16x32_bf16 v[112:115], v[184:187], v[192:195], v[112:115]
	v_mfma_f32_16x16x32_bf16 v[96:99], v[184:187], v[204:207], v[96:99]
	v_mfma_f32_16x16x32_bf16 v[100:103], v[164:167], v[204:207], v[100:103]
	v_mfma_f32_16x16x32_bf16 v[84:87], v[164:167], v[212:215], v[84:87]
	v_mfma_f32_16x16x32_bf16 v[80:83], v[184:187], v[212:215], v[80:83]
	v_mfma_f32_16x16x32_bf16 v[64:67], v[184:187], v[220:223], v[64:67]
	v_mfma_f32_16x16x32_bf16 v[68:71], v[164:167], v[220:223], v[68:71]
	v_mfma_f32_16x16x32_bf16 v[116:119], v[180:183], v[196:199], v[116:119]
	v_mfma_f32_16x16x32_bf16 v[112:115], v[188:191], v[196:199], v[112:115]
	v_mfma_f32_16x16x32_bf16 v[96:99], v[188:191], v[208:211], v[96:99]
	v_mfma_f32_16x16x32_bf16 v[100:103], v[180:183], v[208:211], v[100:103]
	v_mfma_f32_16x16x32_bf16 v[84:87], v[180:183], v[216:219], v[84:87]
	v_mfma_f32_16x16x32_bf16 v[80:83], v[188:191], v[216:219], v[80:83]
	v_mfma_f32_16x16x32_bf16 v[64:67], v[188:191], v[224:227], v[64:67]
	v_mfma_f32_16x16x32_bf16 v[68:71], v[180:183], v[224:227], v[68:71]
	s_setprio 0
	s_barrier
	s_add_i32 s54, s67, s31
	v_lshl_add_u64 v[168:169], v[168:169], 0, s[22:23]
	s_mov_b32 m0, s54
	ds_read_b128 v[192:195], v175 offset:49152
	ds_read_b128 v[196:199], v175 offset:50176
	ds_read_b128 v[204:207], v175 offset:51200
	ds_read_b128 v[208:211], v175 offset:52224
	ds_read_b128 v[212:215], v175 offset:53248
	ds_read_b128 v[216:219], v175 offset:54272
	ds_read_b128 v[220:223], v175 offset:55296
	ds_read_b128 v[224:227], v175 offset:56320
	global_load_lds_dwordx4 v[168:169], off
	s_add_i32 m0, s54, 0x2000
	s_add_u32 s52, s52, 0x40080
	v_lshl_add_u64 v[168:169], v[200:201], 0, s[22:23]
	s_addc_u32 s53, s53, 0
	s_add_i32 s54, s68, s31
	global_load_lds_dwordx4 v[168:169], off
	v_lshl_add_u64 v[168:169], s[52:53], 0, v[130:131]
	s_mov_b32 m0, s54
	s_nop 0
	global_load_lds_dwordx4 v[168:169], off
	v_lshl_add_u64 v[168:169], s[52:53], 0, v[134:135]
	s_add_i32 m0, s54, 0x2000
	s_nop 0
	global_load_lds_dwordx4 v[168:169], off
	v_lshl_add_u64 v[168:169], v[228:229], 0, s[22:23]
	s_mov_b32 m0, s60
	s_nop 0
	global_load_lds_dwordx4 v[168:169], off
	v_lshl_add_u64 v[168:169], v[230:231], 0, s[22:23]
	s_mov_b32 m0, s61
	s_nop 0
	global_load_lds_dwordx4 v[168:169], off
	s_waitcnt vmcnt(8)
	s_waitcnt lgkmcnt(0)
	s_barrier
	s_setprio 1
	s_waitcnt lgkmcnt(0)
	v_mfma_f32_16x16x32_bf16 v[60:63], v[148:151], v[192:195], v[60:63]
	v_mfma_f32_16x16x32_bf16 v[56:59], v[156:159], v[192:195], v[56:59]
	v_mfma_f32_16x16x32_bf16 v[40:43], v[156:159], v[204:207], v[40:43]
	v_mfma_f32_16x16x32_bf16 v[44:47], v[148:151], v[204:207], v[44:47]
	v_mfma_f32_16x16x32_bf16 v[28:31], v[148:151], v[212:215], v[28:31]
	v_mfma_f32_16x16x32_bf16 v[24:27], v[156:159], v[212:215], v[24:27]
	v_mfma_f32_16x16x32_bf16 v[8:11], v[156:159], v[220:223], v[8:11]
	v_mfma_f32_16x16x32_bf16 v[12:15], v[148:151], v[220:223], v[12:15]
	v_mfma_f32_16x16x32_bf16 v[60:63], v[152:155], v[196:199], v[60:63]
	v_mfma_f32_16x16x32_bf16 v[56:59], v[160:163], v[196:199], v[56:59]
	v_mfma_f32_16x16x32_bf16 v[40:43], v[160:163], v[208:211], v[40:43]
	v_mfma_f32_16x16x32_bf16 v[44:47], v[152:155], v[208:211], v[44:47]
	v_mfma_f32_16x16x32_bf16 v[28:31], v[152:155], v[216:219], v[28:31]
	v_mfma_f32_16x16x32_bf16 v[24:27], v[160:163], v[216:219], v[24:27]
	v_mfma_f32_16x16x32_bf16 v[8:11], v[160:163], v[224:227], v[8:11]
	v_mfma_f32_16x16x32_bf16 v[12:15], v[152:155], v[224:227], v[12:15]
	s_setprio 0
	s_setprio 1
	v_mfma_f32_16x16x32_bf16 v[52:55], v[164:167], v[192:195], v[52:55]
	v_mfma_f32_16x16x32_bf16 v[48:51], v[184:187], v[192:195], v[48:51]
	v_mfma_f32_16x16x32_bf16 v[32:35], v[184:187], v[204:207], v[32:35]
	v_mfma_f32_16x16x32_bf16 v[36:39], v[164:167], v[204:207], v[36:39]
	v_mfma_f32_16x16x32_bf16 v[20:23], v[164:167], v[212:215], v[20:23]
	v_mfma_f32_16x16x32_bf16 v[16:19], v[184:187], v[212:215], v[16:19]
	v_mfma_f32_16x16x32_bf16 v[0:3], v[184:187], v[220:223], v[0:3]
	v_mfma_f32_16x16x32_bf16 v[4:7], v[164:167], v[220:223], v[4:7]
	v_mfma_f32_16x16x32_bf16 v[52:55], v[180:183], v[196:199], v[52:55]
	v_mfma_f32_16x16x32_bf16 v[48:51], v[188:191], v[196:199], v[48:51]
	v_mfma_f32_16x16x32_bf16 v[32:35], v[188:191], v[208:211], v[32:35]
	v_mfma_f32_16x16x32_bf16 v[36:39], v[180:183], v[208:211], v[36:39]
	v_mfma_f32_16x16x32_bf16 v[20:23], v[180:183], v[216:219], v[20:23]
	v_mfma_f32_16x16x32_bf16 v[16:19], v[188:191], v[216:219], v[16:19]
	v_mfma_f32_16x16x32_bf16 v[0:3], v[188:191], v[224:227], v[0:3]
	v_mfma_f32_16x16x32_bf16 v[4:7], v[180:183], v[224:227], v[4:7]
	s_setprio 0
	s_barrier
	s_add_i32 s66, s66, 2
	s_add_u32 s50, s50, 0x100
	s_addc_u32 s51, s51, 0
	s_add_u32 s43, s43, 0x100
	s_addc_u32 s45, s45, 0
	s_cmp_gt_u32 s66, 13
	s_cbranch_scc0 .LBB0_220
	s_and_b64 vcc, exec, s[24:25]
	s_cbranch_vccz .LBB0_223
	s_barrier

.LBB0_401:
	ds_read_b128 v[128:131], v189
	ds_read_b128 v[132:135], v189 offset:1024
	ds_read_b128 v[136:139], v189 offset:2048
	ds_read_b128 v[140:143], v189 offset:3072
	ds_read_b128 v[144:147], v190
	ds_read_b128 v[148:151], v190 offset:1024
	ds_read_b128 v[168:171], v190 offset:2048
	ds_read_b128 v[172:175], v190 offset:3072
	s_add_u32 s4, s42, 0xfff80080
	s_addc_u32 s5, s43, -1
	s_cmp_eq_u32 s59, 28
	s_cselect_b32 s45, s35, s5
	s_cselect_b32 s44, s41, s4
	s_cselect_b32 s5, s31, s58
	s_cselect_b32 s4, s56, s57
	v_lshl_add_u64 v[184:185], s[42:43], 0, v[160:161]
	s_add_i32 m0, s47, 0xc000
	ds_read_b128 v[176:179], v191
	ds_read_b128 v[180:183], v191 offset:1024
	ds_read_b128 v[194:197], v191 offset:2048
	ds_read_b128 v[198:201], v191 offset:3072
	ds_read_b128 v[204:207], v191 offset:4096
	ds_read_b128 v[208:211], v191 offset:5120
	ds_read_b128 v[212:215], v191 offset:6144
	ds_read_b128 v[216:219], v191 offset:7168
	global_load_lds_dwordx4 v[184:185], off
	v_lshl_add_u64 v[184:185], s[42:43], 0, v[162:163]
	s_add_i32 m0, s47, 0xe000
	s_nop 0
	global_load_lds_dwordx4 v[184:185], off
	s_waitcnt vmcnt(8)
	s_waitcnt lgkmcnt(0)
	s_barrier
	s_setprio 1
	s_waitcnt lgkmcnt(0)
	v_mfma_f32_16x16x32_bf16 v[124:127], v[128:131], v[176:179], v[124:127]
	v_mfma_f32_16x16x32_bf16 v[120:123], v[136:139], v[176:179], v[120:123]
	v_mfma_f32_16x16x32_bf16 v[104:107], v[136:139], v[194:197], v[104:107]
	v_mfma_f32_16x16x32_bf16 v[108:111], v[128:131], v[194:197], v[108:111]
	v_mfma_f32_16x16x32_bf16 v[92:95], v[128:131], v[204:207], v[92:95]
	v_mfma_f32_16x16x32_bf16 v[88:91], v[136:139], v[204:207], v[88:91]
	v_mfma_f32_16x16x32_bf16 v[72:75], v[136:139], v[212:215], v[72:75]
	v_mfma_f32_16x16x32_bf16 v[76:79], v[128:131], v[212:215], v[76:79]
	v_mfma_f32_16x16x32_bf16 v[124:127], v[132:135], v[180:183], v[124:127]
	v_mfma_f32_16x16x32_bf16 v[120:123], v[140:143], v[180:183], v[120:123]
	v_mfma_f32_16x16x32_bf16 v[104:107], v[140:143], v[198:201], v[104:107]
	v_mfma_f32_16x16x32_bf16 v[108:111], v[132:135], v[198:201], v[108:111]
	v_mfma_f32_16x16x32_bf16 v[92:95], v[132:135], v[208:211], v[92:95]
	v_mfma_f32_16x16x32_bf16 v[88:91], v[140:143], v[208:211], v[88:91]
	v_mfma_f32_16x16x32_bf16 v[72:75], v[140:143], v[216:219], v[72:75]
	v_mfma_f32_16x16x32_bf16 v[76:79], v[132:135], v[216:219], v[76:79]
	s_setprio 0
	s_setprio 1
	v_mfma_f32_16x16x32_bf16 v[116:119], v[144:147], v[176:179], v[116:119]
	v_mfma_f32_16x16x32_bf16 v[112:115], v[168:171], v[176:179], v[112:115]
	v_mfma_f32_16x16x32_bf16 v[96:99], v[168:171], v[194:197], v[96:99]
	v_mfma_f32_16x16x32_bf16 v[100:103], v[144:147], v[194:197], v[100:103]
	v_mfma_f32_16x16x32_bf16 v[84:87], v[144:147], v[204:207], v[84:87]
	v_mfma_f32_16x16x32_bf16 v[80:83], v[168:171], v[204:207], v[80:83]
	v_mfma_f32_16x16x32_bf16 v[64:67], v[168:171], v[212:215], v[64:67]
	v_mfma_f32_16x16x32_bf16 v[68:71], v[144:147], v[212:215], v[68:71]
	v_mfma_f32_16x16x32_bf16 v[116:119], v[148:151], v[180:183], v[116:119]
	v_mfma_f32_16x16x32_bf16 v[112:115], v[172:175], v[180:183], v[112:115]
	v_mfma_f32_16x16x32_bf16 v[96:99], v[172:175], v[198:201], v[96:99]
	v_mfma_f32_16x16x32_bf16 v[100:103], v[148:151], v[198:201], v[100:103]
	v_mfma_f32_16x16x32_bf16 v[84:87], v[148:151], v[208:211], v[84:87]
	v_mfma_f32_16x16x32_bf16 v[80:83], v[172:175], v[208:211], v[80:83]
	v_mfma_f32_16x16x32_bf16 v[64:67], v[172:175], v[216:219], v[64:67]
	v_mfma_f32_16x16x32_bf16 v[68:71], v[148:151], v[216:219], v[68:71]
	s_setprio 0
	s_barrier
	s_add_i32 s60, s53, s46
	v_lshl_add_u64 v[184:185], s[4:5], 0, v[154:155]
	s_mov_b32 m0, s60
	ds_read_b128 v[176:179], v191 offset:16384
	ds_read_b128 v[180:183], v191 offset:17408
	ds_read_b128 v[194:197], v191 offset:18432
	ds_read_b128 v[198:201], v191 offset:19456
	ds_read_b128 v[204:207], v191 offset:20480
	ds_read_b128 v[208:211], v191 offset:21504
	ds_read_b128 v[212:215], v191 offset:22528
	ds_read_b128 v[216:219], v191 offset:23552
	global_load_lds_dwordx4 v[184:185], off
	s_add_i32 m0, s60, 0x2000
	s_add_u32 s60, s4, 0x80000
	v_lshl_add_u64 v[220:221], s[4:5], 0, v[158:159]
	s_addc_u32 s61, s5, 0
	s_add_i32 s62, s54, s46
	global_load_lds_dwordx4 v[220:221], off
	v_lshl_add_u64 v[222:223], s[60:61], 0, v[154:155]
	s_mov_b32 m0, s62
	v_lshl_add_u64 v[224:225], s[44:45], 0, v[156:157]
	global_load_lds_dwordx4 v[222:223], off
	v_lshl_add_u64 v[222:223], s[60:61], 0, v[158:159]
	s_add_i32 m0, s62, 0x2000
	s_nop 0
	global_load_lds_dwordx4 v[222:223], off
	v_lshl_add_u64 v[222:223], s[44:45], 0, v[152:153]
	s_mov_b32 m0, s47
	s_nop 0
	global_load_lds_dwordx4 v[222:223], off
	s_mov_b32 m0, s48
	s_nop 0
	global_load_lds_dwordx4 v[224:225], off
	s_waitcnt vmcnt(8)
	s_waitcnt lgkmcnt(0)
	s_barrier
	s_setprio 1
	s_waitcnt lgkmcnt(0)
	v_mfma_f32_16x16x32_bf16 v[60:63], v[128:131], v[176:179], v[60:63]
	v_mfma_f32_16x16x32_bf16 v[56:59], v[136:139], v[176:179], v[56:59]
	v_mfma_f32_16x16x32_bf16 v[40:43], v[136:139], v[194:197], v[40:43]
	v_mfma_f32_16x16x32_bf16 v[44:47], v[128:131], v[194:197], v[44:47]
	v_mfma_f32_16x16x32_bf16 v[28:31], v[128:131], v[204:207], v[28:31]
	v_mfma_f32_16x16x32_bf16 v[24:27], v[136:139], v[204:207], v[24:27]
	v_mfma_f32_16x16x32_bf16 v[8:11], v[136:139], v[212:215], v[8:11]
	v_mfma_f32_16x16x32_bf16 v[12:15], v[128:131], v[212:215], v[12:15]
	v_mfma_f32_16x16x32_bf16 v[60:63], v[132:135], v[180:183], v[60:63]
	v_mfma_f32_16x16x32_bf16 v[56:59], v[140:143], v[180:183], v[56:59]
	v_mfma_f32_16x16x32_bf16 v[40:43], v[140:143], v[198:201], v[40:43]
	v_mfma_f32_16x16x32_bf16 v[44:47], v[132:135], v[198:201], v[44:47]
	v_mfma_f32_16x16x32_bf16 v[28:31], v[132:135], v[208:211], v[28:31]
	v_mfma_f32_16x16x32_bf16 v[24:27], v[140:143], v[208:211], v[24:27]
	v_mfma_f32_16x16x32_bf16 v[8:11], v[140:143], v[216:219], v[8:11]
	v_mfma_f32_16x16x32_bf16 v[12:15], v[132:135], v[216:219], v[12:15]
	s_setprio 0
	s_setprio 1
	v_mfma_f32_16x16x32_bf16 v[52:55], v[144:147], v[176:179], v[52:55]
	v_mfma_f32_16x16x32_bf16 v[48:51], v[168:171], v[176:179], v[48:51]
	v_mfma_f32_16x16x32_bf16 v[32:35], v[168:171], v[194:197], v[32:35]
	v_mfma_f32_16x16x32_bf16 v[36:39], v[144:147], v[194:197], v[36:39]
	v_mfma_f32_16x16x32_bf16 v[20:23], v[144:147], v[204:207], v[20:23]
	v_mfma_f32_16x16x32_bf16 v[16:19], v[168:171], v[204:207], v[16:19]
	v_mfma_f32_16x16x32_bf16 v[0:3], v[168:171], v[212:215], v[0:3]
	v_mfma_f32_16x16x32_bf16 v[4:7], v[144:147], v[212:215], v[4:7]
	v_mfma_f32_16x16x32_bf16 v[52:55], v[148:151], v[180:183], v[52:55]
	v_mfma_f32_16x16x32_bf16 v[48:51], v[172:175], v[180:183], v[48:51]
	v_mfma_f32_16x16x32_bf16 v[32:35], v[172:175], v[198:201], v[32:35]
	v_mfma_f32_16x16x32_bf16 v[36:39], v[148:151], v[198:201], v[36:39]
	v_mfma_f32_16x16x32_bf16 v[20:23], v[148:151], v[208:211], v[20:23]
	v_mfma_f32_16x16x32_bf16 v[16:19], v[172:175], v[208:211], v[16:19]
	v_mfma_f32_16x16x32_bf16 v[0:3], v[172:175], v[216:219], v[0:3]
	v_mfma_f32_16x16x32_bf16 v[4:7], v[148:151], v[216:219], v[4:7]
	s_setprio 0
	s_barrier
	s_add_i32 s60, 0, 0x18000
	s_add_i32 s61, 0, 0x1c000
	v_add_u32_e32 v140, s60, v187
	v_add_u32_e32 v172, s61, v187
	ds_read_b128 v[128:131], v140
	ds_read_b128 v[132:135], v140 offset:1024
	ds_read_b128 v[136:139], v140 offset:2048
	ds_read_b128 v[140:143], v140 offset:3072
	ds_read_b128 v[144:147], v172
	ds_read_b128 v[148:151], v172 offset:1024
	ds_read_b128 v[168:171], v172 offset:2048
	ds_read_b128 v[172:175], v172 offset:3072
	s_add_u32 s44, s44, 0x80000
	s_addc_u32 s45, s45, 0
	s_mov_b32 m0, s49
	v_lshl_add_u64 v[226:227], s[44:45], 0, v[152:153]
	ds_read_b128 v[176:179], v191 offset:32768
	ds_read_b128 v[180:183], v191 offset:33792
	ds_read_b128 v[194:197], v191 offset:34816
	ds_read_b128 v[198:201], v191 offset:35840
	ds_read_b128 v[204:207], v191 offset:36864
	ds_read_b128 v[208:211], v191 offset:37888
	ds_read_b128 v[212:215], v191 offset:38912
	ds_read_b128 v[216:219], v191 offset:39936
	global_load_lds_dwordx4 v[226:227], off
	v_lshl_add_u64 v[226:227], s[44:45], 0, v[156:157]
	s_mov_b32 m0, s50
	s_nop 0
	global_load_lds_dwordx4 v[226:227], off
	s_waitcnt vmcnt(8)
	s_waitcnt lgkmcnt(0)
	s_barrier
	s_setprio 1
	s_waitcnt lgkmcnt(0)
	v_mfma_f32_16x16x32_bf16 v[124:127], v[128:131], v[176:179], v[124:127]
	v_mfma_f32_16x16x32_bf16 v[120:123], v[136:139], v[176:179], v[120:123]
	v_mfma_f32_16x16x32_bf16 v[104:107], v[136:139], v[194:197], v[104:107]
	v_mfma_f32_16x16x32_bf16 v[108:111], v[128:131], v[194:197], v[108:111]
	v_mfma_f32_16x16x32_bf16 v[92:95], v[128:131], v[204:207], v[92:95]
	v_mfma_f32_16x16x32_bf16 v[88:91], v[136:139], v[204:207], v[88:91]
	v_mfma_f32_16x16x32_bf16 v[72:75], v[136:139], v[212:215], v[72:75]
	v_mfma_f32_16x16x32_bf16 v[76:79], v[128:131], v[212:215], v[76:79]
	v_mfma_f32_16x16x32_bf16 v[124:127], v[132:135], v[180:183], v[124:127]
	v_mfma_f32_16x16x32_bf16 v[120:123], v[140:143], v[180:183], v[120:123]
	v_mfma_f32_16x16x32_bf16 v[104:107], v[140:143], v[198:201], v[104:107]
	v_mfma_f32_16x16x32_bf16 v[108:111], v[132:135], v[198:201], v[108:111]
	v_mfma_f32_16x16x32_bf16 v[92:95], v[132:135], v[208:211], v[92:95]
	v_mfma_f32_16x16x32_bf16 v[88:91], v[140:143], v[208:211], v[88:91]
	v_mfma_f32_16x16x32_bf16 v[72:75], v[140:143], v[216:219], v[72:75]
	v_mfma_f32_16x16x32_bf16 v[76:79], v[132:135], v[216:219], v[76:79]
	s_setprio 0
	s_setprio 1
	v_mfma_f32_16x16x32_bf16 v[116:119], v[144:147], v[176:179], v[116:119]
	v_mfma_f32_16x16x32_bf16 v[112:115], v[168:171], v[176:179], v[112:115]
	v_mfma_f32_16x16x32_bf16 v[96:99], v[168:171], v[194:197], v[96:99]
	v_mfma_f32_16x16x32_bf16 v[100:103], v[144:147], v[194:197], v[100:103]
	v_mfma_f32_16x16x32_bf16 v[84:87], v[144:147], v[204:207], v[84:87]
	v_mfma_f32_16x16x32_bf16 v[80:83], v[168:171], v[204:207], v[80:83]
	v_mfma_f32_16x16x32_bf16 v[64:67], v[168:171], v[212:215], v[64:67]
	v_mfma_f32_16x16x32_bf16 v[68:71], v[144:147], v[212:215], v[68:71]
	v_mfma_f32_16x16x32_bf16 v[116:119], v[148:151], v[180:183], v[116:119]
	v_mfma_f32_16x16x32_bf16 v[112:115], v[172:175], v[180:183], v[112:115]
	v_mfma_f32_16x16x32_bf16 v[96:99], v[172:175], v[198:201], v[96:99]
	v_mfma_f32_16x16x32_bf16 v[100:103], v[148:151], v[198:201], v[100:103]
	v_mfma_f32_16x16x32_bf16 v[84:87], v[148:151], v[208:211], v[84:87]
	v_mfma_f32_16x16x32_bf16 v[80:83], v[172:175], v[208:211], v[80:83]
	v_mfma_f32_16x16x32_bf16 v[64:67], v[172:175], v[216:219], v[64:67]
	v_mfma_f32_16x16x32_bf16 v[68:71], v[148:151], v[216:219], v[68:71]
	s_setprio 0
	s_barrier
	s_add_i32 s44, s60, s46
	v_lshl_add_u64 v[184:185], v[184:185], 0, s[26:27]
	s_mov_b32 m0, s44
	ds_read_b128 v[176:179], v191 offset:49152
	ds_read_b128 v[180:183], v191 offset:50176
	ds_read_b128 v[194:197], v191 offset:51200
	ds_read_b128 v[198:201], v191 offset:52224
	ds_read_b128 v[204:207], v191 offset:53248
	ds_read_b128 v[208:211], v191 offset:54272
	ds_read_b128 v[212:215], v191 offset:55296
	ds_read_b128 v[216:219], v191 offset:56320
	global_load_lds_dwordx4 v[184:185], off
	s_add_i32 m0, s44, 0x2000
	s_add_u32 s4, s4, 0x80080
	v_lshl_add_u64 v[184:185], v[220:221], 0, s[26:27]
	s_addc_u32 s5, s5, 0
	s_add_i32 s44, s61, s46
	global_load_lds_dwordx4 v[184:185], off
	v_lshl_add_u64 v[184:185], s[4:5], 0, v[154:155]
	s_mov_b32 m0, s44
	s_nop 0
	global_load_lds_dwordx4 v[184:185], off
	v_lshl_add_u64 v[184:185], s[4:5], 0, v[158:159]
	s_add_i32 m0, s44, 0x2000
	s_nop 0
	global_load_lds_dwordx4 v[184:185], off
	v_lshl_add_u64 v[184:185], v[222:223], 0, s[26:27]
	s_mov_b32 m0, s33
	s_nop 0
	global_load_lds_dwordx4 v[184:185], off
	v_lshl_add_u64 v[184:185], v[224:225], 0, s[26:27]
	s_mov_b32 m0, s52
	s_nop 0
	global_load_lds_dwordx4 v[184:185], off
	s_waitcnt vmcnt(8)
	s_waitcnt lgkmcnt(0)
	s_barrier
	s_setprio 1
	s_waitcnt lgkmcnt(0)
	v_mfma_f32_16x16x32_bf16 v[60:63], v[128:131], v[176:179], v[60:63]
	v_mfma_f32_16x16x32_bf16 v[56:59], v[136:139], v[176:179], v[56:59]
	v_mfma_f32_16x16x32_bf16 v[40:43], v[136:139], v[194:197], v[40:43]
	v_mfma_f32_16x16x32_bf16 v[44:47], v[128:131], v[194:197], v[44:47]
	v_mfma_f32_16x16x32_bf16 v[28:31], v[128:131], v[204:207], v[28:31]
	v_mfma_f32_16x16x32_bf16 v[24:27], v[136:139], v[204:207], v[24:27]
	v_mfma_f32_16x16x32_bf16 v[8:11], v[136:139], v[212:215], v[8:11]
	v_mfma_f32_16x16x32_bf16 v[12:15], v[128:131], v[212:215], v[12:15]
	v_mfma_f32_16x16x32_bf16 v[60:63], v[132:135], v[180:183], v[60:63]
	v_mfma_f32_16x16x32_bf16 v[56:59], v[140:143], v[180:183], v[56:59]
	v_mfma_f32_16x16x32_bf16 v[40:43], v[140:143], v[198:201], v[40:43]
	v_mfma_f32_16x16x32_bf16 v[44:47], v[132:135], v[198:201], v[44:47]
	v_mfma_f32_16x16x32_bf16 v[28:31], v[132:135], v[208:211], v[28:31]
	v_mfma_f32_16x16x32_bf16 v[24:27], v[140:143], v[208:211], v[24:27]
	v_mfma_f32_16x16x32_bf16 v[8:11], v[140:143], v[216:219], v[8:11]
	v_mfma_f32_16x16x32_bf16 v[12:15], v[132:135], v[216:219], v[12:15]
	s_setprio 0
	s_setprio 1
	v_mfma_f32_16x16x32_bf16 v[52:55], v[144:147], v[176:179], v[52:55]
	v_mfma_f32_16x16x32_bf16 v[48:51], v[168:171], v[176:179], v[48:51]
	v_mfma_f32_16x16x32_bf16 v[32:35], v[168:171], v[194:197], v[32:35]
	v_mfma_f32_16x16x32_bf16 v[36:39], v[144:147], v[194:197], v[36:39]
	v_mfma_f32_16x16x32_bf16 v[20:23], v[144:147], v[204:207], v[20:23]
	v_mfma_f32_16x16x32_bf16 v[16:19], v[168:171], v[204:207], v[16:19]
	v_mfma_f32_16x16x32_bf16 v[0:3], v[168:171], v[212:215], v[0:3]
	v_mfma_f32_16x16x32_bf16 v[4:7], v[144:147], v[212:215], v[4:7]
	v_mfma_f32_16x16x32_bf16 v[52:55], v[148:151], v[180:183], v[52:55]
	v_mfma_f32_16x16x32_bf16 v[48:51], v[172:175], v[180:183], v[48:51]
	v_mfma_f32_16x16x32_bf16 v[32:35], v[172:175], v[198:201], v[32:35]
	v_mfma_f32_16x16x32_bf16 v[36:39], v[148:151], v[198:201], v[36:39]
	v_mfma_f32_16x16x32_bf16 v[20:23], v[148:151], v[208:211], v[20:23]
	v_mfma_f32_16x16x32_bf16 v[16:19], v[172:175], v[208:211], v[16:19]
	v_mfma_f32_16x16x32_bf16 v[0:3], v[172:175], v[216:219], v[0:3]
	v_mfma_f32_16x16x32_bf16 v[4:7], v[148:151], v[216:219], v[4:7]
	s_setprio 0
	s_barrier
	s_add_i32 s59, s59, 2
	s_add_u32 s42, s42, 0x100
	s_addc_u32 s43, s43, 0
	s_add_u32 s57, s57, 0x100
	s_addc_u32 s58, s58, 0
	s_cmp_gt_u32 s59, 29
	s_cbranch_scc0 .LBB0_401
	s_and_b64 vcc, exec, s[28:29]
	s_cbranch_vccz .LBB0_404
	s_barrier

.LBB0_483:
	ds_read_b128 v[146:149], v169
	ds_read_b128 v[150:153], v169 offset:1024
	ds_read_b128 v[154:157], v169 offset:2048
	ds_read_b128 v[160:163], v169 offset:3072
	ds_read_b128 v[180:183], v171
	ds_read_b128 v[184:187], v171 offset:1024
	ds_read_b128 v[188:191], v171 offset:2048
	ds_read_b128 v[192:195], v171 offset:3072
	s_add_u32 s4, s10, 0xfffc0080
	s_addc_u32 s5, s11, -1
	s_cmp_eq_u32 s56, 12
	s_cselect_b32 s13, s9, s5
	s_cselect_b32 s12, s37, s4
	s_cselect_b32 s5, s35, s55
	s_cselect_b32 s4, s53, s54
	v_lshl_add_u64 v[200:201], s[10:11], 0, v[138:139]
	s_add_i32 m0, s42, 0xc000
	ds_read_b128 v[196:199], v173
	ds_read_b128 v[204:207], v173 offset:1024
	ds_read_b128 v[208:211], v173 offset:2048
	ds_read_b128 v[212:215], v173 offset:3072
	ds_read_b128 v[216:219], v173 offset:4096
	ds_read_b128 v[220:223], v173 offset:5120
	ds_read_b128 v[224:227], v173 offset:6144
	ds_read_b128 v[228:231], v173 offset:7168
	global_load_lds_dwordx4 v[200:201], off
	v_lshl_add_u64 v[200:201], s[10:11], 0, v[140:141]
	s_add_i32 m0, s42, 0xe000
	s_nop 0
	global_load_lds_dwordx4 v[200:201], off
	s_waitcnt vmcnt(8)
	s_waitcnt lgkmcnt(0)
	s_barrier
	s_setprio 1
	s_waitcnt lgkmcnt(0)
	v_mfma_f32_16x16x32_bf16 v[124:127], v[146:149], v[196:199], v[124:127]
	v_mfma_f32_16x16x32_bf16 v[116:119], v[154:157], v[196:199], v[116:119]
	v_mfma_f32_16x16x32_bf16 v[100:103], v[154:157], v[208:211], v[100:103]
	v_mfma_f32_16x16x32_bf16 v[108:111], v[146:149], v[208:211], v[108:111]
	v_mfma_f32_16x16x32_bf16 v[92:95], v[146:149], v[216:219], v[92:95]
	v_mfma_f32_16x16x32_bf16 v[84:87], v[154:157], v[216:219], v[84:87]
	v_mfma_f32_16x16x32_bf16 v[68:71], v[154:157], v[224:227], v[68:71]
	v_mfma_f32_16x16x32_bf16 v[76:79], v[146:149], v[224:227], v[76:79]
	v_mfma_f32_16x16x32_bf16 v[124:127], v[150:153], v[204:207], v[124:127]
	v_mfma_f32_16x16x32_bf16 v[116:119], v[160:163], v[204:207], v[116:119]
	v_mfma_f32_16x16x32_bf16 v[100:103], v[160:163], v[212:215], v[100:103]
	v_mfma_f32_16x16x32_bf16 v[108:111], v[150:153], v[212:215], v[108:111]
	v_mfma_f32_16x16x32_bf16 v[92:95], v[150:153], v[220:223], v[92:95]
	v_mfma_f32_16x16x32_bf16 v[84:87], v[160:163], v[220:223], v[84:87]
	v_mfma_f32_16x16x32_bf16 v[68:71], v[160:163], v[228:231], v[68:71]
	v_mfma_f32_16x16x32_bf16 v[76:79], v[150:153], v[228:231], v[76:79]
	s_setprio 0
	s_setprio 1
	v_mfma_f32_16x16x32_bf16 v[120:123], v[180:183], v[196:199], v[120:123]
	v_mfma_f32_16x16x32_bf16 v[112:115], v[188:191], v[196:199], v[112:115]
	v_mfma_f32_16x16x32_bf16 v[96:99], v[188:191], v[208:211], v[96:99]
	v_mfma_f32_16x16x32_bf16 v[104:107], v[180:183], v[208:211], v[104:107]
	v_mfma_f32_16x16x32_bf16 v[88:91], v[180:183], v[216:219], v[88:91]
	v_mfma_f32_16x16x32_bf16 v[80:83], v[188:191], v[216:219], v[80:83]
	v_mfma_f32_16x16x32_bf16 v[64:67], v[188:191], v[224:227], v[64:67]
	v_mfma_f32_16x16x32_bf16 v[72:75], v[180:183], v[224:227], v[72:75]
	v_mfma_f32_16x16x32_bf16 v[120:123], v[184:187], v[204:207], v[120:123]
	v_mfma_f32_16x16x32_bf16 v[112:115], v[192:195], v[204:207], v[112:115]
	v_mfma_f32_16x16x32_bf16 v[96:99], v[192:195], v[212:215], v[96:99]
	v_mfma_f32_16x16x32_bf16 v[104:107], v[184:187], v[212:215], v[104:107]
	v_mfma_f32_16x16x32_bf16 v[88:91], v[184:187], v[220:223], v[88:91]
	v_mfma_f32_16x16x32_bf16 v[80:83], v[192:195], v[220:223], v[80:83]
	v_mfma_f32_16x16x32_bf16 v[64:67], v[192:195], v[228:231], v[64:67]
	v_mfma_f32_16x16x32_bf16 v[72:75], v[184:187], v[228:231], v[72:75]
	s_setprio 0
	s_barrier
	s_add_i32 s57, s49, s23
	v_lshl_add_u64 v[200:201], s[4:5], 0, v[132:133]
	s_mov_b32 m0, s57
	ds_read_b128 v[196:199], v173 offset:16384
	ds_read_b128 v[204:207], v173 offset:17408
	ds_read_b128 v[208:211], v173 offset:18432
	ds_read_b128 v[212:215], v173 offset:19456
	ds_read_b128 v[216:219], v173 offset:20480
	ds_read_b128 v[220:223], v173 offset:21504
	ds_read_b128 v[224:227], v173 offset:22528
	ds_read_b128 v[228:231], v173 offset:23552
	global_load_lds_dwordx4 v[200:201], off
	s_add_i32 m0, s57, 0x2000
	s_add_u32 s58, s4, 0x40000
	v_lshl_add_u64 v[232:233], s[4:5], 0, v[128:129]
	s_addc_u32 s59, s5, 0
	s_add_i32 s57, s50, s23
	global_load_lds_dwordx4 v[232:233], off
	v_lshl_add_u64 v[234:235], s[58:59], 0, v[132:133]
	s_mov_b32 m0, s57
	v_lshl_add_u64 v[236:237], s[12:13], 0, v[130:131]
	global_load_lds_dwordx4 v[234:235], off
	v_lshl_add_u64 v[234:235], s[58:59], 0, v[128:129]
	s_add_i32 m0, s57, 0x2000
	s_nop 0
	global_load_lds_dwordx4 v[234:235], off
	v_lshl_add_u64 v[234:235], s[12:13], 0, v[134:135]
	s_mov_b32 m0, s42
	s_nop 0
	global_load_lds_dwordx4 v[234:235], off
	s_mov_b32 m0, s43
	s_nop 0
	global_load_lds_dwordx4 v[236:237], off
	s_waitcnt vmcnt(8)
	s_waitcnt lgkmcnt(0)
	s_barrier
	s_setprio 1
	s_waitcnt lgkmcnt(0)
	v_mfma_f32_16x16x32_bf16 v[60:63], v[146:149], v[196:199], v[60:63]
	v_mfma_f32_16x16x32_bf16 v[52:55], v[154:157], v[196:199], v[52:55]
	v_mfma_f32_16x16x32_bf16 v[36:39], v[154:157], v[208:211], v[36:39]
	v_mfma_f32_16x16x32_bf16 v[44:47], v[146:149], v[208:211], v[44:47]
	v_mfma_f32_16x16x32_bf16 v[28:31], v[146:149], v[216:219], v[28:31]
	v_mfma_f32_16x16x32_bf16 v[20:23], v[154:157], v[216:219], v[20:23]
	v_mfma_f32_16x16x32_bf16 v[4:7], v[154:157], v[224:227], v[4:7]
	v_mfma_f32_16x16x32_bf16 v[12:15], v[146:149], v[224:227], v[12:15]
	v_mfma_f32_16x16x32_bf16 v[60:63], v[150:153], v[204:207], v[60:63]
	v_mfma_f32_16x16x32_bf16 v[52:55], v[160:163], v[204:207], v[52:55]
	v_mfma_f32_16x16x32_bf16 v[36:39], v[160:163], v[212:215], v[36:39]
	v_mfma_f32_16x16x32_bf16 v[44:47], v[150:153], v[212:215], v[44:47]
	v_mfma_f32_16x16x32_bf16 v[28:31], v[150:153], v[220:223], v[28:31]
	v_mfma_f32_16x16x32_bf16 v[20:23], v[160:163], v[220:223], v[20:23]
	v_mfma_f32_16x16x32_bf16 v[4:7], v[160:163], v[228:231], v[4:7]
	v_mfma_f32_16x16x32_bf16 v[12:15], v[150:153], v[228:231], v[12:15]
	s_setprio 0
	s_setprio 1
	v_mfma_f32_16x16x32_bf16 v[56:59], v[180:183], v[196:199], v[56:59]
	v_mfma_f32_16x16x32_bf16 v[48:51], v[188:191], v[196:199], v[48:51]
	v_mfma_f32_16x16x32_bf16 v[32:35], v[188:191], v[208:211], v[32:35]
	v_mfma_f32_16x16x32_bf16 v[40:43], v[180:183], v[208:211], v[40:43]
	v_mfma_f32_16x16x32_bf16 v[24:27], v[180:183], v[216:219], v[24:27]
	v_mfma_f32_16x16x32_bf16 v[16:19], v[188:191], v[216:219], v[16:19]
	v_mfma_f32_16x16x32_bf16 v[0:3], v[188:191], v[224:227], v[0:3]
	v_mfma_f32_16x16x32_bf16 v[8:11], v[180:183], v[224:227], v[8:11]
	v_mfma_f32_16x16x32_bf16 v[56:59], v[184:187], v[204:207], v[56:59]
	v_mfma_f32_16x16x32_bf16 v[48:51], v[192:195], v[204:207], v[48:51]
	v_mfma_f32_16x16x32_bf16 v[32:35], v[192:195], v[212:215], v[32:35]
	v_mfma_f32_16x16x32_bf16 v[40:43], v[184:187], v[212:215], v[40:43]
	v_mfma_f32_16x16x32_bf16 v[24:27], v[184:187], v[220:223], v[24:27]
	v_mfma_f32_16x16x32_bf16 v[16:19], v[192:195], v[220:223], v[16:19]
	v_mfma_f32_16x16x32_bf16 v[0:3], v[192:195], v[228:231], v[0:3]
	v_mfma_f32_16x16x32_bf16 v[8:11], v[184:187], v[228:231], v[8:11]
	s_setprio 0
	s_barrier
	s_add_i32 s57, 0, 0x18000
	v_add_u32_e32 v158, s57, v165
	s_add_i32 s58, 0, 0x1c000
	ds_read_b128 v[146:149], v158
	ds_read_b128 v[150:153], v158 offset:1024
	ds_read_b128 v[154:157], v158 offset:2048
	ds_read_b128 v[160:163], v158 offset:3072
	v_add_u32_e32 v158, s58, v165
	ds_read_b128 v[180:183], v158
	ds_read_b128 v[184:187], v158 offset:1024
	ds_read_b128 v[188:191], v158 offset:2048
	ds_read_b128 v[192:195], v158 offset:3072
	s_add_u32 s12, s12, 0x40000
	s_addc_u32 s13, s13, 0
	s_mov_b32 m0, s44
	v_lshl_add_u64 v[238:239], s[12:13], 0, v[134:135]
	ds_read_b128 v[196:199], v173 offset:32768
	ds_read_b128 v[204:207], v173 offset:33792
	ds_read_b128 v[208:211], v173 offset:34816
	ds_read_b128 v[212:215], v173 offset:35840
	ds_read_b128 v[216:219], v173 offset:36864
	ds_read_b128 v[220:223], v173 offset:37888
	ds_read_b128 v[224:227], v173 offset:38912
	ds_read_b128 v[228:231], v173 offset:39936
	global_load_lds_dwordx4 v[238:239], off
	v_lshl_add_u64 v[238:239], s[12:13], 0, v[130:131]
	s_mov_b32 m0, s45
	s_nop 0
	global_load_lds_dwordx4 v[238:239], off
	s_waitcnt vmcnt(8)
	s_waitcnt lgkmcnt(0)
	s_barrier
	s_setprio 1
	s_waitcnt lgkmcnt(0)
	v_mfma_f32_16x16x32_bf16 v[124:127], v[146:149], v[196:199], v[124:127]
	v_mfma_f32_16x16x32_bf16 v[116:119], v[154:157], v[196:199], v[116:119]
	v_mfma_f32_16x16x32_bf16 v[100:103], v[154:157], v[208:211], v[100:103]
	v_mfma_f32_16x16x32_bf16 v[108:111], v[146:149], v[208:211], v[108:111]
	v_mfma_f32_16x16x32_bf16 v[92:95], v[146:149], v[216:219], v[92:95]
	v_mfma_f32_16x16x32_bf16 v[84:87], v[154:157], v[216:219], v[84:87]
	v_mfma_f32_16x16x32_bf16 v[68:71], v[154:157], v[224:227], v[68:71]
	v_mfma_f32_16x16x32_bf16 v[76:79], v[146:149], v[224:227], v[76:79]
	v_mfma_f32_16x16x32_bf16 v[124:127], v[150:153], v[204:207], v[124:127]
	v_mfma_f32_16x16x32_bf16 v[116:119], v[160:163], v[204:207], v[116:119]
	v_mfma_f32_16x16x32_bf16 v[100:103], v[160:163], v[212:215], v[100:103]
	v_mfma_f32_16x16x32_bf16 v[108:111], v[150:153], v[212:215], v[108:111]
	v_mfma_f32_16x16x32_bf16 v[92:95], v[150:153], v[220:223], v[92:95]
	v_mfma_f32_16x16x32_bf16 v[84:87], v[160:163], v[220:223], v[84:87]
	v_mfma_f32_16x16x32_bf16 v[68:71], v[160:163], v[228:231], v[68:71]
	v_mfma_f32_16x16x32_bf16 v[76:79], v[150:153], v[228:231], v[76:79]
	s_setprio 0
	s_setprio 1
	v_mfma_f32_16x16x32_bf16 v[120:123], v[180:183], v[196:199], v[120:123]
	v_mfma_f32_16x16x32_bf16 v[112:115], v[188:191], v[196:199], v[112:115]
	v_mfma_f32_16x16x32_bf16 v[96:99], v[188:191], v[208:211], v[96:99]
	v_mfma_f32_16x16x32_bf16 v[104:107], v[180:183], v[208:211], v[104:107]
	v_mfma_f32_16x16x32_bf16 v[88:91], v[180:183], v[216:219], v[88:91]
	v_mfma_f32_16x16x32_bf16 v[80:83], v[188:191], v[216:219], v[80:83]
	v_mfma_f32_16x16x32_bf16 v[64:67], v[188:191], v[224:227], v[64:67]
	v_mfma_f32_16x16x32_bf16 v[72:75], v[180:183], v[224:227], v[72:75]
	v_mfma_f32_16x16x32_bf16 v[120:123], v[184:187], v[204:207], v[120:123]
	v_mfma_f32_16x16x32_bf16 v[112:115], v[192:195], v[204:207], v[112:115]
	v_mfma_f32_16x16x32_bf16 v[96:99], v[192:195], v[212:215], v[96:99]
	v_mfma_f32_16x16x32_bf16 v[104:107], v[184:187], v[212:215], v[104:107]
	v_mfma_f32_16x16x32_bf16 v[88:91], v[184:187], v[220:223], v[88:91]
	v_mfma_f32_16x16x32_bf16 v[80:83], v[192:195], v[220:223], v[80:83]
	v_mfma_f32_16x16x32_bf16 v[64:67], v[192:195], v[228:231], v[64:67]
	v_mfma_f32_16x16x32_bf16 v[72:75], v[184:187], v[228:231], v[72:75]
	s_setprio 0
	s_barrier
	s_add_i32 s12, s57, s23
	v_lshl_add_u64 v[200:201], v[200:201], 0, s[28:29]
	s_mov_b32 m0, s12
	ds_read_b128 v[196:199], v173 offset:49152
	ds_read_b128 v[204:207], v173 offset:50176
	ds_read_b128 v[208:211], v173 offset:51200
	ds_read_b128 v[212:215], v173 offset:52224
	ds_read_b128 v[216:219], v173 offset:53248
	ds_read_b128 v[220:223], v173 offset:54272
	ds_read_b128 v[224:227], v173 offset:55296
	ds_read_b128 v[228:231], v173 offset:56320
	global_load_lds_dwordx4 v[200:201], off
	s_add_i32 m0, s12, 0x2000
	s_add_u32 s4, s4, 0x40080
	v_lshl_add_u64 v[200:201], v[232:233], 0, s[28:29]
	s_addc_u32 s5, s5, 0
	s_add_i32 s12, s58, s23
	global_load_lds_dwordx4 v[200:201], off
	v_lshl_add_u64 v[200:201], s[4:5], 0, v[132:133]
	s_mov_b32 m0, s12
	s_nop 0
	global_load_lds_dwordx4 v[200:201], off
	v_lshl_add_u64 v[200:201], s[4:5], 0, v[128:129]
	s_add_i32 m0, s12, 0x2000
	s_nop 0
	global_load_lds_dwordx4 v[200:201], off
	v_lshl_add_u64 v[200:201], v[234:235], 0, s[28:29]
	s_mov_b32 m0, s47
	s_nop 0
	global_load_lds_dwordx4 v[200:201], off
	v_lshl_add_u64 v[200:201], v[236:237], 0, s[28:29]
	s_mov_b32 m0, s48
	s_nop 0
	global_load_lds_dwordx4 v[200:201], off
	s_waitcnt vmcnt(8)
	s_waitcnt lgkmcnt(0)
	s_barrier
	s_setprio 1
	s_waitcnt lgkmcnt(0)
	v_mfma_f32_16x16x32_bf16 v[60:63], v[146:149], v[196:199], v[60:63]
	v_mfma_f32_16x16x32_bf16 v[52:55], v[154:157], v[196:199], v[52:55]
	v_mfma_f32_16x16x32_bf16 v[36:39], v[154:157], v[208:211], v[36:39]
	v_mfma_f32_16x16x32_bf16 v[44:47], v[146:149], v[208:211], v[44:47]
	v_mfma_f32_16x16x32_bf16 v[28:31], v[146:149], v[216:219], v[28:31]
	v_mfma_f32_16x16x32_bf16 v[20:23], v[154:157], v[216:219], v[20:23]
	v_mfma_f32_16x16x32_bf16 v[4:7], v[154:157], v[224:227], v[4:7]
	v_mfma_f32_16x16x32_bf16 v[12:15], v[146:149], v[224:227], v[12:15]
	v_mfma_f32_16x16x32_bf16 v[60:63], v[150:153], v[204:207], v[60:63]
	v_mfma_f32_16x16x32_bf16 v[52:55], v[160:163], v[204:207], v[52:55]
	v_mfma_f32_16x16x32_bf16 v[36:39], v[160:163], v[212:215], v[36:39]
	v_mfma_f32_16x16x32_bf16 v[44:47], v[150:153], v[212:215], v[44:47]
	v_mfma_f32_16x16x32_bf16 v[28:31], v[150:153], v[220:223], v[28:31]
	v_mfma_f32_16x16x32_bf16 v[20:23], v[160:163], v[220:223], v[20:23]
	v_mfma_f32_16x16x32_bf16 v[4:7], v[160:163], v[228:231], v[4:7]
	v_mfma_f32_16x16x32_bf16 v[12:15], v[150:153], v[228:231], v[12:15]
	s_setprio 0
	s_setprio 1
	v_mfma_f32_16x16x32_bf16 v[56:59], v[180:183], v[196:199], v[56:59]
	v_mfma_f32_16x16x32_bf16 v[48:51], v[188:191], v[196:199], v[48:51]
	v_mfma_f32_16x16x32_bf16 v[32:35], v[188:191], v[208:211], v[32:35]
	v_mfma_f32_16x16x32_bf16 v[40:43], v[180:183], v[208:211], v[40:43]
	v_mfma_f32_16x16x32_bf16 v[24:27], v[180:183], v[216:219], v[24:27]
	v_mfma_f32_16x16x32_bf16 v[16:19], v[188:191], v[216:219], v[16:19]
	v_mfma_f32_16x16x32_bf16 v[0:3], v[188:191], v[224:227], v[0:3]
	v_mfma_f32_16x16x32_bf16 v[8:11], v[180:183], v[224:227], v[8:11]
	v_mfma_f32_16x16x32_bf16 v[56:59], v[184:187], v[204:207], v[56:59]
	v_mfma_f32_16x16x32_bf16 v[48:51], v[192:195], v[204:207], v[48:51]
	v_mfma_f32_16x16x32_bf16 v[32:35], v[192:195], v[212:215], v[32:35]
	v_mfma_f32_16x16x32_bf16 v[40:43], v[184:187], v[212:215], v[40:43]
	v_mfma_f32_16x16x32_bf16 v[24:27], v[184:187], v[220:223], v[24:27]
	v_mfma_f32_16x16x32_bf16 v[16:19], v[192:195], v[220:223], v[16:19]
	v_mfma_f32_16x16x32_bf16 v[0:3], v[192:195], v[228:231], v[0:3]
	v_mfma_f32_16x16x32_bf16 v[8:11], v[184:187], v[228:231], v[8:11]
	s_setprio 0
	s_barrier
	s_add_i32 s56, s56, 2
	s_add_u32 s10, s10, 0x100
	s_addc_u32 s11, s11, 0
	s_add_u32 s54, s54, 0x100
	s_addc_u32 s55, s55, 0
	s_cmp_gt_u32 s56, 13
	s_cbranch_scc0 .LBB0_483
	s_and_b64 vcc, exec, s[30:31]
	s_cbranch_vccz .LBB0_486
	s_barrier

.LBB0_559:
	ds_read_b128 v[128:131], v189
	ds_read_b128 v[132:135], v189 offset:1024
	ds_read_b128 v[136:139], v189 offset:2048
	ds_read_b128 v[140:143], v189 offset:3072
	ds_read_b128 v[144:147], v190
	ds_read_b128 v[148:151], v190 offset:1024
	ds_read_b128 v[168:171], v190 offset:2048
	ds_read_b128 v[172:175], v190 offset:3072
	s_add_u32 s4, s22, 0x100
	s_addc_u32 s5, s23, 0
	s_cmp_eq_u32 s57, 40
	s_cselect_b32 s41, s11, s5
	s_cselect_b32 s40, s10, s4
	s_cselect_b32 s39, s37, s56
	s_cselect_b32 s38, s36, s55
	v_lshl_add_u64 v[184:185], s[22:23], 0, v[160:161]
	s_add_i32 m0, s43, 0xc000
	ds_read_b128 v[176:179], v191
	ds_read_b128 v[180:183], v191 offset:1024
	ds_read_b128 v[194:197], v191 offset:2048
	ds_read_b128 v[198:201], v191 offset:3072
	ds_read_b128 v[204:207], v191 offset:4096
	ds_read_b128 v[208:211], v191 offset:5120
	ds_read_b128 v[212:215], v191 offset:6144
	ds_read_b128 v[216:219], v191 offset:7168
	global_load_lds_dwordx4 v[184:185], off
	v_lshl_add_u64 v[184:185], s[22:23], 0, v[162:163]
	s_add_i32 m0, s43, 0xe000
	s_nop 0
	global_load_lds_dwordx4 v[184:185], off
	s_waitcnt vmcnt(8)
	s_waitcnt lgkmcnt(0)
	s_barrier
	s_setprio 1
	s_waitcnt lgkmcnt(0)
	v_mfma_f32_16x16x32_bf16 v[124:127], v[128:131], v[176:179], v[124:127]
	v_mfma_f32_16x16x32_bf16 v[120:123], v[136:139], v[176:179], v[120:123]
	v_mfma_f32_16x16x32_bf16 v[104:107], v[136:139], v[194:197], v[104:107]
	v_mfma_f32_16x16x32_bf16 v[108:111], v[128:131], v[194:197], v[108:111]
	v_mfma_f32_16x16x32_bf16 v[92:95], v[128:131], v[204:207], v[92:95]
	v_mfma_f32_16x16x32_bf16 v[88:91], v[136:139], v[204:207], v[88:91]
	v_mfma_f32_16x16x32_bf16 v[72:75], v[136:139], v[212:215], v[72:75]
	v_mfma_f32_16x16x32_bf16 v[76:79], v[128:131], v[212:215], v[76:79]
	v_mfma_f32_16x16x32_bf16 v[124:127], v[132:135], v[180:183], v[124:127]
	v_mfma_f32_16x16x32_bf16 v[120:123], v[140:143], v[180:183], v[120:123]
	v_mfma_f32_16x16x32_bf16 v[104:107], v[140:143], v[198:201], v[104:107]
	v_mfma_f32_16x16x32_bf16 v[108:111], v[132:135], v[198:201], v[108:111]
	v_mfma_f32_16x16x32_bf16 v[92:95], v[132:135], v[208:211], v[92:95]
	v_mfma_f32_16x16x32_bf16 v[88:91], v[140:143], v[208:211], v[88:91]
	v_mfma_f32_16x16x32_bf16 v[72:75], v[140:143], v[216:219], v[72:75]
	v_mfma_f32_16x16x32_bf16 v[76:79], v[132:135], v[216:219], v[76:79]
	s_setprio 0
	s_setprio 1
	v_mfma_f32_16x16x32_bf16 v[116:119], v[144:147], v[176:179], v[116:119]
	v_mfma_f32_16x16x32_bf16 v[112:115], v[168:171], v[176:179], v[112:115]
	v_mfma_f32_16x16x32_bf16 v[96:99], v[168:171], v[194:197], v[96:99]
	v_mfma_f32_16x16x32_bf16 v[100:103], v[144:147], v[194:197], v[100:103]
	v_mfma_f32_16x16x32_bf16 v[84:87], v[144:147], v[204:207], v[84:87]
	v_mfma_f32_16x16x32_bf16 v[80:83], v[168:171], v[204:207], v[80:83]
	v_mfma_f32_16x16x32_bf16 v[64:67], v[168:171], v[212:215], v[64:67]
	v_mfma_f32_16x16x32_bf16 v[68:71], v[144:147], v[212:215], v[68:71]
	v_mfma_f32_16x16x32_bf16 v[116:119], v[148:151], v[180:183], v[116:119]
	v_mfma_f32_16x16x32_bf16 v[112:115], v[172:175], v[180:183], v[112:115]
	v_mfma_f32_16x16x32_bf16 v[96:99], v[172:175], v[198:201], v[96:99]
	v_mfma_f32_16x16x32_bf16 v[100:103], v[148:151], v[198:201], v[100:103]
	v_mfma_f32_16x16x32_bf16 v[84:87], v[148:151], v[208:211], v[84:87]
	v_mfma_f32_16x16x32_bf16 v[80:83], v[172:175], v[208:211], v[80:83]
	v_mfma_f32_16x16x32_bf16 v[64:67], v[172:175], v[216:219], v[64:67]
	v_mfma_f32_16x16x32_bf16 v[68:71], v[148:151], v[216:219], v[68:71]
	s_setprio 0
	s_barrier
	s_add_i32 s22, s49, s42
	v_lshl_add_u64 v[184:185], s[38:39], 0, v[154:155]
	s_mov_b32 m0, s22
	ds_read_b128 v[176:179], v191 offset:16384
	ds_read_b128 v[180:183], v191 offset:17408
	ds_read_b128 v[194:197], v191 offset:18432
	ds_read_b128 v[198:201], v191 offset:19456
	ds_read_b128 v[204:207], v191 offset:20480
	ds_read_b128 v[208:211], v191 offset:21504
	ds_read_b128 v[212:215], v191 offset:22528
	ds_read_b128 v[216:219], v191 offset:23552
	global_load_lds_dwordx4 v[184:185], off
	s_add_i32 m0, s22, 0x2000
	s_add_u32 s22, s38, 0xb0000
	v_lshl_add_u64 v[220:221], s[38:39], 0, v[158:159]
	s_addc_u32 s23, s39, 0
	s_add_i32 s58, s50, s42
	global_load_lds_dwordx4 v[220:221], off
	v_lshl_add_u64 v[222:223], s[22:23], 0, v[154:155]
	s_mov_b32 m0, s58
	v_lshl_add_u64 v[224:225], s[40:41], 0, v[156:157]
	global_load_lds_dwordx4 v[222:223], off
	v_lshl_add_u64 v[222:223], s[22:23], 0, v[158:159]
	s_add_i32 m0, s58, 0x2000
	s_nop 0
	global_load_lds_dwordx4 v[222:223], off
	v_lshl_add_u64 v[222:223], s[40:41], 0, v[152:153]
	s_mov_b32 m0, s43
	s_nop 0
	global_load_lds_dwordx4 v[222:223], off
	s_mov_b32 m0, s44
	s_nop 0
	global_load_lds_dwordx4 v[224:225], off
	s_waitcnt vmcnt(8)
	s_waitcnt lgkmcnt(0)
	s_barrier
	s_setprio 1
	s_waitcnt lgkmcnt(0)
	v_mfma_f32_16x16x32_bf16 v[60:63], v[128:131], v[176:179], v[60:63]
	v_mfma_f32_16x16x32_bf16 v[56:59], v[136:139], v[176:179], v[56:59]
	v_mfma_f32_16x16x32_bf16 v[40:43], v[136:139], v[194:197], v[40:43]
	v_mfma_f32_16x16x32_bf16 v[44:47], v[128:131], v[194:197], v[44:47]
	v_mfma_f32_16x16x32_bf16 v[28:31], v[128:131], v[204:207], v[28:31]
	v_mfma_f32_16x16x32_bf16 v[24:27], v[136:139], v[204:207], v[24:27]
	v_mfma_f32_16x16x32_bf16 v[8:11], v[136:139], v[212:215], v[8:11]
	v_mfma_f32_16x16x32_bf16 v[12:15], v[128:131], v[212:215], v[12:15]
	v_mfma_f32_16x16x32_bf16 v[60:63], v[132:135], v[180:183], v[60:63]
	v_mfma_f32_16x16x32_bf16 v[56:59], v[140:143], v[180:183], v[56:59]
	v_mfma_f32_16x16x32_bf16 v[40:43], v[140:143], v[198:201], v[40:43]
	v_mfma_f32_16x16x32_bf16 v[44:47], v[132:135], v[198:201], v[44:47]
	v_mfma_f32_16x16x32_bf16 v[28:31], v[132:135], v[208:211], v[28:31]
	v_mfma_f32_16x16x32_bf16 v[24:27], v[140:143], v[208:211], v[24:27]
	v_mfma_f32_16x16x32_bf16 v[8:11], v[140:143], v[216:219], v[8:11]
	v_mfma_f32_16x16x32_bf16 v[12:15], v[132:135], v[216:219], v[12:15]
	s_setprio 0
	s_setprio 1
	v_mfma_f32_16x16x32_bf16 v[52:55], v[144:147], v[176:179], v[52:55]
	v_mfma_f32_16x16x32_bf16 v[48:51], v[168:171], v[176:179], v[48:51]
	v_mfma_f32_16x16x32_bf16 v[32:35], v[168:171], v[194:197], v[32:35]
	v_mfma_f32_16x16x32_bf16 v[36:39], v[144:147], v[194:197], v[36:39]
	v_mfma_f32_16x16x32_bf16 v[20:23], v[144:147], v[204:207], v[20:23]
	v_mfma_f32_16x16x32_bf16 v[16:19], v[168:171], v[204:207], v[16:19]
	v_mfma_f32_16x16x32_bf16 v[0:3], v[168:171], v[212:215], v[0:3]
	v_mfma_f32_16x16x32_bf16 v[4:7], v[144:147], v[212:215], v[4:7]
	v_mfma_f32_16x16x32_bf16 v[52:55], v[148:151], v[180:183], v[52:55]
	v_mfma_f32_16x16x32_bf16 v[48:51], v[172:175], v[180:183], v[48:51]
	v_mfma_f32_16x16x32_bf16 v[32:35], v[172:175], v[198:201], v[32:35]
	v_mfma_f32_16x16x32_bf16 v[36:39], v[148:151], v[198:201], v[36:39]
	v_mfma_f32_16x16x32_bf16 v[20:23], v[148:151], v[208:211], v[20:23]
	v_mfma_f32_16x16x32_bf16 v[16:19], v[172:175], v[208:211], v[16:19]
	v_mfma_f32_16x16x32_bf16 v[0:3], v[172:175], v[216:219], v[0:3]
	v_mfma_f32_16x16x32_bf16 v[4:7], v[148:151], v[216:219], v[4:7]
	s_setprio 0
	s_barrier
	s_add_i32 s58, 0, 0x18000
	s_add_i32 s59, 0, 0x1c000
	v_add_u32_e32 v140, s58, v187
	v_add_u32_e32 v172, s59, v187
	ds_read_b128 v[128:131], v140
	ds_read_b128 v[132:135], v140 offset:1024
	ds_read_b128 v[136:139], v140 offset:2048
	ds_read_b128 v[140:143], v140 offset:3072
	ds_read_b128 v[144:147], v172
	ds_read_b128 v[148:151], v172 offset:1024
	ds_read_b128 v[168:171], v172 offset:2048
	ds_read_b128 v[172:175], v172 offset:3072
	s_add_u32 s22, s40, 0xb0000
	s_addc_u32 s23, s41, 0
	s_mov_b32 m0, s45
	v_lshl_add_u64 v[226:227], s[22:23], 0, v[152:153]
	ds_read_b128 v[176:179], v191 offset:32768
	ds_read_b128 v[180:183], v191 offset:33792
	ds_read_b128 v[194:197], v191 offset:34816
	ds_read_b128 v[198:201], v191 offset:35840
	ds_read_b128 v[204:207], v191 offset:36864
	ds_read_b128 v[208:211], v191 offset:37888
	ds_read_b128 v[212:215], v191 offset:38912
	ds_read_b128 v[216:219], v191 offset:39936
	global_load_lds_dwordx4 v[226:227], off
	v_lshl_add_u64 v[226:227], s[22:23], 0, v[156:157]
	s_mov_b32 m0, s46
	s_nop 0
	global_load_lds_dwordx4 v[226:227], off
	s_waitcnt vmcnt(8)
	s_waitcnt lgkmcnt(0)
	s_barrier
	s_setprio 1
	s_waitcnt lgkmcnt(0)
	v_mfma_f32_16x16x32_bf16 v[124:127], v[128:131], v[176:179], v[124:127]
	v_mfma_f32_16x16x32_bf16 v[120:123], v[136:139], v[176:179], v[120:123]
	v_mfma_f32_16x16x32_bf16 v[104:107], v[136:139], v[194:197], v[104:107]
	v_mfma_f32_16x16x32_bf16 v[108:111], v[128:131], v[194:197], v[108:111]
	v_mfma_f32_16x16x32_bf16 v[92:95], v[128:131], v[204:207], v[92:95]
	v_mfma_f32_16x16x32_bf16 v[88:91], v[136:139], v[204:207], v[88:91]
	v_mfma_f32_16x16x32_bf16 v[72:75], v[136:139], v[212:215], v[72:75]
	v_mfma_f32_16x16x32_bf16 v[76:79], v[128:131], v[212:215], v[76:79]
	v_mfma_f32_16x16x32_bf16 v[124:127], v[132:135], v[180:183], v[124:127]
	v_mfma_f32_16x16x32_bf16 v[120:123], v[140:143], v[180:183], v[120:123]
	v_mfma_f32_16x16x32_bf16 v[104:107], v[140:143], v[198:201], v[104:107]
	v_mfma_f32_16x16x32_bf16 v[108:111], v[132:135], v[198:201], v[108:111]
	v_mfma_f32_16x16x32_bf16 v[92:95], v[132:135], v[208:211], v[92:95]
	v_mfma_f32_16x16x32_bf16 v[88:91], v[140:143], v[208:211], v[88:91]
	v_mfma_f32_16x16x32_bf16 v[72:75], v[140:143], v[216:219], v[72:75]
	v_mfma_f32_16x16x32_bf16 v[76:79], v[132:135], v[216:219], v[76:79]
	s_setprio 0
	s_setprio 1
	v_mfma_f32_16x16x32_bf16 v[116:119], v[144:147], v[176:179], v[116:119]
	v_mfma_f32_16x16x32_bf16 v[112:115], v[168:171], v[176:179], v[112:115]
	v_mfma_f32_16x16x32_bf16 v[96:99], v[168:171], v[194:197], v[96:99]
	v_mfma_f32_16x16x32_bf16 v[100:103], v[144:147], v[194:197], v[100:103]
	v_mfma_f32_16x16x32_bf16 v[84:87], v[144:147], v[204:207], v[84:87]
	v_mfma_f32_16x16x32_bf16 v[80:83], v[168:171], v[204:207], v[80:83]
	v_mfma_f32_16x16x32_bf16 v[64:67], v[168:171], v[212:215], v[64:67]
	v_mfma_f32_16x16x32_bf16 v[68:71], v[144:147], v[212:215], v[68:71]
	v_mfma_f32_16x16x32_bf16 v[116:119], v[148:151], v[180:183], v[116:119]
	v_mfma_f32_16x16x32_bf16 v[112:115], v[172:175], v[180:183], v[112:115]
	v_mfma_f32_16x16x32_bf16 v[96:99], v[172:175], v[198:201], v[96:99]
	v_mfma_f32_16x16x32_bf16 v[100:103], v[148:151], v[198:201], v[100:103]
	v_mfma_f32_16x16x32_bf16 v[84:87], v[148:151], v[208:211], v[84:87]
	v_mfma_f32_16x16x32_bf16 v[80:83], v[172:175], v[208:211], v[80:83]
	v_mfma_f32_16x16x32_bf16 v[64:67], v[172:175], v[216:219], v[64:67]
	v_mfma_f32_16x16x32_bf16 v[68:71], v[148:151], v[216:219], v[68:71]
	s_setprio 0
	s_barrier
	s_add_i32 s22, s58, s42
	v_lshl_add_u64 v[184:185], v[184:185], 0, s[30:31]
	s_mov_b32 m0, s22
	ds_read_b128 v[176:179], v191 offset:49152
	ds_read_b128 v[180:183], v191 offset:50176
	ds_read_b128 v[194:197], v191 offset:51200
	ds_read_b128 v[198:201], v191 offset:52224
	ds_read_b128 v[204:207], v191 offset:53248
	ds_read_b128 v[208:211], v191 offset:54272
	ds_read_b128 v[212:215], v191 offset:55296
	ds_read_b128 v[216:219], v191 offset:56320
	global_load_lds_dwordx4 v[184:185], off
	s_add_i32 m0, s22, 0x2000
	s_add_u32 s22, s38, 0xb0080
	v_lshl_add_u64 v[184:185], v[220:221], 0, s[30:31]
	s_addc_u32 s23, s39, 0
	s_add_i32 s38, s59, s42
	global_load_lds_dwordx4 v[184:185], off
	v_lshl_add_u64 v[184:185], s[22:23], 0, v[154:155]
	s_mov_b32 m0, s38
	s_nop 0
	global_load_lds_dwordx4 v[184:185], off
	v_lshl_add_u64 v[184:185], s[22:23], 0, v[158:159]
	s_add_i32 m0, s38, 0x2000
	s_nop 0
	global_load_lds_dwordx4 v[184:185], off
	v_lshl_add_u64 v[184:185], v[222:223], 0, s[30:31]
	s_mov_b32 m0, s33
	s_nop 0
	global_load_lds_dwordx4 v[184:185], off
	v_lshl_add_u64 v[184:185], v[224:225], 0, s[30:31]
	s_mov_b32 m0, s48
	s_nop 0
	global_load_lds_dwordx4 v[184:185], off
	s_waitcnt vmcnt(8)
	s_waitcnt lgkmcnt(0)
	s_barrier
	s_setprio 1
	s_waitcnt lgkmcnt(0)
	v_mfma_f32_16x16x32_bf16 v[60:63], v[128:131], v[176:179], v[60:63]
	v_mfma_f32_16x16x32_bf16 v[56:59], v[136:139], v[176:179], v[56:59]
	v_mfma_f32_16x16x32_bf16 v[40:43], v[136:139], v[194:197], v[40:43]
	v_mfma_f32_16x16x32_bf16 v[44:47], v[128:131], v[194:197], v[44:47]
	v_mfma_f32_16x16x32_bf16 v[28:31], v[128:131], v[204:207], v[28:31]
	v_mfma_f32_16x16x32_bf16 v[24:27], v[136:139], v[204:207], v[24:27]
	v_mfma_f32_16x16x32_bf16 v[8:11], v[136:139], v[212:215], v[8:11]
	v_mfma_f32_16x16x32_bf16 v[12:15], v[128:131], v[212:215], v[12:15]
	v_mfma_f32_16x16x32_bf16 v[60:63], v[132:135], v[180:183], v[60:63]
	v_mfma_f32_16x16x32_bf16 v[56:59], v[140:143], v[180:183], v[56:59]
	v_mfma_f32_16x16x32_bf16 v[40:43], v[140:143], v[198:201], v[40:43]
	v_mfma_f32_16x16x32_bf16 v[44:47], v[132:135], v[198:201], v[44:47]
	v_mfma_f32_16x16x32_bf16 v[28:31], v[132:135], v[208:211], v[28:31]
	v_mfma_f32_16x16x32_bf16 v[24:27], v[140:143], v[208:211], v[24:27]
	v_mfma_f32_16x16x32_bf16 v[8:11], v[140:143], v[216:219], v[8:11]
	v_mfma_f32_16x16x32_bf16 v[12:15], v[132:135], v[216:219], v[12:15]
	s_setprio 0
	s_setprio 1
	v_mfma_f32_16x16x32_bf16 v[52:55], v[144:147], v[176:179], v[52:55]
	v_mfma_f32_16x16x32_bf16 v[48:51], v[168:171], v[176:179], v[48:51]
	v_mfma_f32_16x16x32_bf16 v[32:35], v[168:171], v[194:197], v[32:35]
	v_mfma_f32_16x16x32_bf16 v[36:39], v[144:147], v[194:197], v[36:39]
	v_mfma_f32_16x16x32_bf16 v[20:23], v[144:147], v[204:207], v[20:23]
	v_mfma_f32_16x16x32_bf16 v[16:19], v[168:171], v[204:207], v[16:19]
	v_mfma_f32_16x16x32_bf16 v[0:3], v[168:171], v[212:215], v[0:3]
	v_mfma_f32_16x16x32_bf16 v[4:7], v[144:147], v[212:215], v[4:7]
	v_mfma_f32_16x16x32_bf16 v[52:55], v[148:151], v[180:183], v[52:55]
	v_mfma_f32_16x16x32_bf16 v[48:51], v[172:175], v[180:183], v[48:51]
	v_mfma_f32_16x16x32_bf16 v[32:35], v[172:175], v[198:201], v[32:35]
	v_mfma_f32_16x16x32_bf16 v[36:39], v[148:151], v[198:201], v[36:39]
	v_mfma_f32_16x16x32_bf16 v[20:23], v[148:151], v[208:211], v[20:23]
	v_mfma_f32_16x16x32_bf16 v[16:19], v[172:175], v[208:211], v[16:19]
	v_mfma_f32_16x16x32_bf16 v[0:3], v[172:175], v[216:219], v[0:3]
	v_mfma_f32_16x16x32_bf16 v[4:7], v[148:151], v[216:219], v[4:7]
	s_setprio 0
	s_barrier
	s_add_i32 s57, s57, 2
	s_add_u32 s55, s55, 0x100
	s_addc_u32 s56, s56, 0
	s_cmp_gt_u32 s57, 41
	s_mov_b64 s[22:23], s[4:5]
	s_cbranch_scc0 .LBB0_559
	s_and_b64 vcc, exec, s[34:35]
	s_cbranch_vccz .LBB0_562
	s_barrier

.LBB0_643:
	ds_read_b128 v[128:131], v191
	ds_read_b128 v[132:135], v191 offset:1024
	ds_read_b128 v[156:159], v191 offset:2048
	ds_read_b128 v[160:163], v191 offset:3072
	ds_read_b128 v[164:167], v192
	ds_read_b128 v[168:171], v192 offset:1024
	ds_read_b128 v[172:175], v192 offset:2048
	ds_read_b128 v[176:179], v192 offset:3072
	s_add_u32 s4, s22, 0xfffc0080
	s_addc_u32 s5, s23, -1
	s_cmp_eq_u32 s63, 12
	s_cselect_b32 s47, s13, s5
	s_cselect_b32 s46, s17, s4
	s_cselect_b32 s5, s33, s62
	s_cselect_b32 s4, s39, s41
	v_lshl_add_u64 v[224:225], s[22:23], 0, v[148:149]
	s_add_i32 m0, s49, 0xc000
	ds_read_b128 v[180:183], v193
	ds_read_b128 v[184:187], v193 offset:1024
	ds_read_b128 v[198:201], v193 offset:2048
	ds_read_b128 v[204:207], v193 offset:3072
	ds_read_b128 v[208:211], v193 offset:4096
	ds_read_b128 v[212:215], v193 offset:5120
	ds_read_b128 v[216:219], v193 offset:6144
	ds_read_b128 v[220:223], v193 offset:7168
	global_load_lds_dwordx4 v[224:225], off
	v_lshl_add_u64 v[224:225], s[22:23], 0, v[150:151]
	s_add_i32 m0, s49, 0xe000
	s_nop 0
	global_load_lds_dwordx4 v[224:225], off
	s_waitcnt vmcnt(8)
	s_waitcnt lgkmcnt(0)
	s_barrier
	s_setprio 1
	s_waitcnt lgkmcnt(0)
	v_mfma_f32_16x16x32_bf16 v[124:127], v[128:131], v[180:183], v[124:127]
	v_mfma_f32_16x16x32_bf16 v[120:123], v[156:159], v[180:183], v[120:123]
	v_mfma_f32_16x16x32_bf16 v[104:107], v[156:159], v[198:201], v[104:107]
	v_mfma_f32_16x16x32_bf16 v[108:111], v[128:131], v[198:201], v[108:111]
	v_mfma_f32_16x16x32_bf16 v[92:95], v[128:131], v[208:211], v[92:95]
	v_mfma_f32_16x16x32_bf16 v[88:91], v[156:159], v[208:211], v[88:91]
	v_mfma_f32_16x16x32_bf16 v[72:75], v[156:159], v[216:219], v[72:75]
	v_mfma_f32_16x16x32_bf16 v[76:79], v[128:131], v[216:219], v[76:79]
	v_mfma_f32_16x16x32_bf16 v[124:127], v[132:135], v[184:187], v[124:127]
	v_mfma_f32_16x16x32_bf16 v[120:123], v[160:163], v[184:187], v[120:123]
	v_mfma_f32_16x16x32_bf16 v[104:107], v[160:163], v[204:207], v[104:107]
	v_mfma_f32_16x16x32_bf16 v[108:111], v[132:135], v[204:207], v[108:111]
	v_mfma_f32_16x16x32_bf16 v[92:95], v[132:135], v[212:215], v[92:95]
	v_mfma_f32_16x16x32_bf16 v[88:91], v[160:163], v[212:215], v[88:91]
	v_mfma_f32_16x16x32_bf16 v[72:75], v[160:163], v[220:223], v[72:75]
	v_mfma_f32_16x16x32_bf16 v[76:79], v[132:135], v[220:223], v[76:79]
	s_setprio 0
	s_setprio 1
	v_mfma_f32_16x16x32_bf16 v[116:119], v[164:167], v[180:183], v[116:119]
	v_mfma_f32_16x16x32_bf16 v[112:115], v[172:175], v[180:183], v[112:115]
	v_mfma_f32_16x16x32_bf16 v[96:99], v[172:175], v[198:201], v[96:99]
	v_mfma_f32_16x16x32_bf16 v[100:103], v[164:167], v[198:201], v[100:103]
	v_mfma_f32_16x16x32_bf16 v[84:87], v[164:167], v[208:211], v[84:87]
	v_mfma_f32_16x16x32_bf16 v[80:83], v[172:175], v[208:211], v[80:83]
	v_mfma_f32_16x16x32_bf16 v[64:67], v[172:175], v[216:219], v[64:67]
	v_mfma_f32_16x16x32_bf16 v[68:71], v[164:167], v[216:219], v[68:71]
	v_mfma_f32_16x16x32_bf16 v[116:119], v[168:171], v[184:187], v[116:119]
	v_mfma_f32_16x16x32_bf16 v[112:115], v[176:179], v[184:187], v[112:115]
	v_mfma_f32_16x16x32_bf16 v[96:99], v[176:179], v[204:207], v[96:99]
	v_mfma_f32_16x16x32_bf16 v[100:103], v[168:171], v[204:207], v[100:103]
	v_mfma_f32_16x16x32_bf16 v[84:87], v[168:171], v[212:215], v[84:87]
	v_mfma_f32_16x16x32_bf16 v[80:83], v[176:179], v[212:215], v[80:83]
	v_mfma_f32_16x16x32_bf16 v[64:67], v[176:179], v[220:223], v[64:67]
	v_mfma_f32_16x16x32_bf16 v[68:71], v[168:171], v[220:223], v[68:71]
	s_setprio 0
	s_barrier
	s_add_i32 s64, s59, s48
	v_lshl_add_u64 v[224:225], s[4:5], 0, v[138:139]
	s_mov_b32 m0, s64
	ds_read_b128 v[180:183], v193 offset:16384
	ds_read_b128 v[184:187], v193 offset:17408
	ds_read_b128 v[198:201], v193 offset:18432
	ds_read_b128 v[204:207], v193 offset:19456
	ds_read_b128 v[208:211], v193 offset:20480
	ds_read_b128 v[212:215], v193 offset:21504
	ds_read_b128 v[216:219], v193 offset:22528
	ds_read_b128 v[220:223], v193 offset:23552
	global_load_lds_dwordx4 v[224:225], off
	s_add_i32 m0, s64, 0x2000
	s_add_u32 s64, s4, 0x40000
	v_lshl_add_u64 v[226:227], s[4:5], 0, v[142:143]
	s_addc_u32 s65, s5, 0
	s_add_i32 s66, s60, s48
	global_load_lds_dwordx4 v[226:227], off
	v_lshl_add_u64 v[228:229], s[64:65], 0, v[138:139]
	s_mov_b32 m0, s66
	v_lshl_add_u64 v[230:231], s[46:47], 0, v[140:141]
	global_load_lds_dwordx4 v[228:229], off
	v_lshl_add_u64 v[228:229], s[64:65], 0, v[142:143]
	s_add_i32 m0, s66, 0x2000
	s_nop 0
	global_load_lds_dwordx4 v[228:229], off
	v_lshl_add_u64 v[228:229], s[46:47], 0, v[136:137]
	s_mov_b32 m0, s49
	s_nop 0
	global_load_lds_dwordx4 v[228:229], off
	s_mov_b32 m0, s50
	s_nop 0
	global_load_lds_dwordx4 v[230:231], off
	s_waitcnt vmcnt(8)
	s_waitcnt lgkmcnt(0)
	s_barrier
	s_setprio 1
	s_waitcnt lgkmcnt(0)
	v_mfma_f32_16x16x32_bf16 v[60:63], v[128:131], v[180:183], v[60:63]
	v_mfma_f32_16x16x32_bf16 v[56:59], v[156:159], v[180:183], v[56:59]
	v_mfma_f32_16x16x32_bf16 v[40:43], v[156:159], v[198:201], v[40:43]
	v_mfma_f32_16x16x32_bf16 v[44:47], v[128:131], v[198:201], v[44:47]
	v_mfma_f32_16x16x32_bf16 v[28:31], v[128:131], v[208:211], v[28:31]
	v_mfma_f32_16x16x32_bf16 v[24:27], v[156:159], v[208:211], v[24:27]
	v_mfma_f32_16x16x32_bf16 v[8:11], v[156:159], v[216:219], v[8:11]
	v_mfma_f32_16x16x32_bf16 v[12:15], v[128:131], v[216:219], v[12:15]
	v_mfma_f32_16x16x32_bf16 v[60:63], v[132:135], v[184:187], v[60:63]
	v_mfma_f32_16x16x32_bf16 v[56:59], v[160:163], v[184:187], v[56:59]
	v_mfma_f32_16x16x32_bf16 v[40:43], v[160:163], v[204:207], v[40:43]
	v_mfma_f32_16x16x32_bf16 v[44:47], v[132:135], v[204:207], v[44:47]
	v_mfma_f32_16x16x32_bf16 v[28:31], v[132:135], v[212:215], v[28:31]
	v_mfma_f32_16x16x32_bf16 v[24:27], v[160:163], v[212:215], v[24:27]
	v_mfma_f32_16x16x32_bf16 v[8:11], v[160:163], v[220:223], v[8:11]
	v_mfma_f32_16x16x32_bf16 v[12:15], v[132:135], v[220:223], v[12:15]
	s_setprio 0
	s_setprio 1
	v_mfma_f32_16x16x32_bf16 v[52:55], v[164:167], v[180:183], v[52:55]
	v_mfma_f32_16x16x32_bf16 v[48:51], v[172:175], v[180:183], v[48:51]
	v_mfma_f32_16x16x32_bf16 v[32:35], v[172:175], v[198:201], v[32:35]
	v_mfma_f32_16x16x32_bf16 v[36:39], v[164:167], v[198:201], v[36:39]
	v_mfma_f32_16x16x32_bf16 v[20:23], v[164:167], v[208:211], v[20:23]
	v_mfma_f32_16x16x32_bf16 v[16:19], v[172:175], v[208:211], v[16:19]
	v_mfma_f32_16x16x32_bf16 v[0:3], v[172:175], v[216:219], v[0:3]
	v_mfma_f32_16x16x32_bf16 v[4:7], v[164:167], v[216:219], v[4:7]
	v_mfma_f32_16x16x32_bf16 v[52:55], v[168:171], v[184:187], v[52:55]
	v_mfma_f32_16x16x32_bf16 v[48:51], v[176:179], v[184:187], v[48:51]
	v_mfma_f32_16x16x32_bf16 v[32:35], v[176:179], v[204:207], v[32:35]
	v_mfma_f32_16x16x32_bf16 v[36:39], v[168:171], v[204:207], v[36:39]
	v_mfma_f32_16x16x32_bf16 v[20:23], v[168:171], v[212:215], v[20:23]
	v_mfma_f32_16x16x32_bf16 v[16:19], v[176:179], v[212:215], v[16:19]
	v_mfma_f32_16x16x32_bf16 v[0:3], v[176:179], v[220:223], v[0:3]
	v_mfma_f32_16x16x32_bf16 v[4:7], v[168:171], v[220:223], v[4:7]
	s_setprio 0
	s_barrier
	s_add_i32 s64, 0, 0x18000
	v_add_u32_e32 v144, s64, v189
	s_add_i32 s65, 0, 0x1c000
	ds_read_b128 v[128:131], v144
	ds_read_b128 v[132:135], v144 offset:1024
	ds_read_b128 v[156:159], v144 offset:2048
	ds_read_b128 v[160:163], v144 offset:3072
	v_add_u32_e32 v144, s65, v189
	ds_read_b128 v[164:167], v144
	ds_read_b128 v[168:171], v144 offset:1024
	ds_read_b128 v[172:175], v144 offset:2048
	ds_read_b128 v[176:179], v144 offset:3072
	s_add_u32 s46, s46, 0x40000
	s_addc_u32 s47, s47, 0
	s_mov_b32 m0, s51
	v_lshl_add_u64 v[232:233], s[46:47], 0, v[136:137]
	ds_read_b128 v[180:183], v193 offset:32768
	ds_read_b128 v[184:187], v193 offset:33792
	ds_read_b128 v[198:201], v193 offset:34816
	ds_read_b128 v[204:207], v193 offset:35840
	ds_read_b128 v[208:211], v193 offset:36864
	ds_read_b128 v[212:215], v193 offset:37888
	ds_read_b128 v[216:219], v193 offset:38912
	ds_read_b128 v[220:223], v193 offset:39936
	global_load_lds_dwordx4 v[232:233], off
	v_lshl_add_u64 v[232:233], s[46:47], 0, v[140:141]
	s_mov_b32 m0, s52
	s_nop 0
	global_load_lds_dwordx4 v[232:233], off
	s_waitcnt vmcnt(8)
	s_waitcnt lgkmcnt(0)
	s_barrier
	s_setprio 1
	s_waitcnt lgkmcnt(0)
	v_mfma_f32_16x16x32_bf16 v[124:127], v[128:131], v[180:183], v[124:127]
	v_mfma_f32_16x16x32_bf16 v[120:123], v[156:159], v[180:183], v[120:123]
	v_mfma_f32_16x16x32_bf16 v[104:107], v[156:159], v[198:201], v[104:107]
	v_mfma_f32_16x16x32_bf16 v[108:111], v[128:131], v[198:201], v[108:111]
	v_mfma_f32_16x16x32_bf16 v[92:95], v[128:131], v[208:211], v[92:95]
	v_mfma_f32_16x16x32_bf16 v[88:91], v[156:159], v[208:211], v[88:91]
	v_mfma_f32_16x16x32_bf16 v[72:75], v[156:159], v[216:219], v[72:75]
	v_mfma_f32_16x16x32_bf16 v[76:79], v[128:131], v[216:219], v[76:79]
	v_mfma_f32_16x16x32_bf16 v[124:127], v[132:135], v[184:187], v[124:127]
	v_mfma_f32_16x16x32_bf16 v[120:123], v[160:163], v[184:187], v[120:123]
	v_mfma_f32_16x16x32_bf16 v[104:107], v[160:163], v[204:207], v[104:107]
	v_mfma_f32_16x16x32_bf16 v[108:111], v[132:135], v[204:207], v[108:111]
	v_mfma_f32_16x16x32_bf16 v[92:95], v[132:135], v[212:215], v[92:95]
	v_mfma_f32_16x16x32_bf16 v[88:91], v[160:163], v[212:215], v[88:91]
	v_mfma_f32_16x16x32_bf16 v[72:75], v[160:163], v[220:223], v[72:75]
	v_mfma_f32_16x16x32_bf16 v[76:79], v[132:135], v[220:223], v[76:79]
	s_setprio 0
	s_setprio 1
	v_mfma_f32_16x16x32_bf16 v[116:119], v[164:167], v[180:183], v[116:119]
	v_mfma_f32_16x16x32_bf16 v[112:115], v[172:175], v[180:183], v[112:115]
	v_mfma_f32_16x16x32_bf16 v[96:99], v[172:175], v[198:201], v[96:99]
	v_mfma_f32_16x16x32_bf16 v[100:103], v[164:167], v[198:201], v[100:103]
	v_mfma_f32_16x16x32_bf16 v[84:87], v[164:167], v[208:211], v[84:87]
	v_mfma_f32_16x16x32_bf16 v[80:83], v[172:175], v[208:211], v[80:83]
	v_mfma_f32_16x16x32_bf16 v[64:67], v[172:175], v[216:219], v[64:67]
	v_mfma_f32_16x16x32_bf16 v[68:71], v[164:167], v[216:219], v[68:71]
	v_mfma_f32_16x16x32_bf16 v[116:119], v[168:171], v[184:187], v[116:119]
	v_mfma_f32_16x16x32_bf16 v[112:115], v[176:179], v[184:187], v[112:115]
	v_mfma_f32_16x16x32_bf16 v[96:99], v[176:179], v[204:207], v[96:99]
	v_mfma_f32_16x16x32_bf16 v[100:103], v[168:171], v[204:207], v[100:103]
	v_mfma_f32_16x16x32_bf16 v[84:87], v[168:171], v[212:215], v[84:87]
	v_mfma_f32_16x16x32_bf16 v[80:83], v[176:179], v[212:215], v[80:83]
	v_mfma_f32_16x16x32_bf16 v[64:67], v[176:179], v[220:223], v[64:67]
	v_mfma_f32_16x16x32_bf16 v[68:71], v[168:171], v[220:223], v[68:71]
	s_setprio 0
	s_barrier
	s_add_i32 s46, s64, s48
	v_lshl_add_u64 v[224:225], v[224:225], 0, s[30:31]
	s_mov_b32 m0, s46
	ds_read_b128 v[180:183], v193 offset:49152
	ds_read_b128 v[184:187], v193 offset:50176
	ds_read_b128 v[198:201], v193 offset:51200
	ds_read_b128 v[204:207], v193 offset:52224
	ds_read_b128 v[208:211], v193 offset:53248
	ds_read_b128 v[212:215], v193 offset:54272
	ds_read_b128 v[216:219], v193 offset:55296
	ds_read_b128 v[220:223], v193 offset:56320
	global_load_lds_dwordx4 v[224:225], off
	s_add_i32 m0, s46, 0x2000
	s_add_u32 s4, s4, 0x40080
	v_lshl_add_u64 v[224:225], v[226:227], 0, s[30:31]
	s_addc_u32 s5, s5, 0
	s_add_i32 s46, s65, s48
	global_load_lds_dwordx4 v[224:225], off
	v_lshl_add_u64 v[224:225], s[4:5], 0, v[138:139]
	s_mov_b32 m0, s46
	s_nop 0
	global_load_lds_dwordx4 v[224:225], off
	v_lshl_add_u64 v[224:225], s[4:5], 0, v[142:143]
	s_add_i32 m0, s46, 0x2000
	s_nop 0
	global_load_lds_dwordx4 v[224:225], off
	v_lshl_add_u64 v[224:225], v[228:229], 0, s[30:31]
	s_mov_b32 m0, s56
	s_nop 0
	global_load_lds_dwordx4 v[224:225], off
	v_lshl_add_u64 v[224:225], v[230:231], 0, s[30:31]
	s_mov_b32 m0, s57
	s_nop 0
	global_load_lds_dwordx4 v[224:225], off
	s_waitcnt vmcnt(8)
	s_waitcnt lgkmcnt(0)
	s_barrier
	s_setprio 1
	s_waitcnt lgkmcnt(0)
	v_mfma_f32_16x16x32_bf16 v[60:63], v[128:131], v[180:183], v[60:63]
	v_mfma_f32_16x16x32_bf16 v[56:59], v[156:159], v[180:183], v[56:59]
	v_mfma_f32_16x16x32_bf16 v[40:43], v[156:159], v[198:201], v[40:43]
	v_mfma_f32_16x16x32_bf16 v[44:47], v[128:131], v[198:201], v[44:47]
	v_mfma_f32_16x16x32_bf16 v[28:31], v[128:131], v[208:211], v[28:31]
	v_mfma_f32_16x16x32_bf16 v[24:27], v[156:159], v[208:211], v[24:27]
	v_mfma_f32_16x16x32_bf16 v[8:11], v[156:159], v[216:219], v[8:11]
	v_mfma_f32_16x16x32_bf16 v[12:15], v[128:131], v[216:219], v[12:15]
	v_mfma_f32_16x16x32_bf16 v[60:63], v[132:135], v[184:187], v[60:63]
	v_mfma_f32_16x16x32_bf16 v[56:59], v[160:163], v[184:187], v[56:59]
	v_mfma_f32_16x16x32_bf16 v[40:43], v[160:163], v[204:207], v[40:43]
	v_mfma_f32_16x16x32_bf16 v[44:47], v[132:135], v[204:207], v[44:47]
	v_mfma_f32_16x16x32_bf16 v[28:31], v[132:135], v[212:215], v[28:31]
	v_mfma_f32_16x16x32_bf16 v[24:27], v[160:163], v[212:215], v[24:27]
	v_mfma_f32_16x16x32_bf16 v[8:11], v[160:163], v[220:223], v[8:11]
	v_mfma_f32_16x16x32_bf16 v[12:15], v[132:135], v[220:223], v[12:15]
	s_setprio 0
	s_setprio 1
	v_mfma_f32_16x16x32_bf16 v[52:55], v[164:167], v[180:183], v[52:55]
	v_mfma_f32_16x16x32_bf16 v[48:51], v[172:175], v[180:183], v[48:51]
	v_mfma_f32_16x16x32_bf16 v[32:35], v[172:175], v[198:201], v[32:35]
	v_mfma_f32_16x16x32_bf16 v[36:39], v[164:167], v[198:201], v[36:39]
	v_mfma_f32_16x16x32_bf16 v[20:23], v[164:167], v[208:211], v[20:23]
	v_mfma_f32_16x16x32_bf16 v[16:19], v[172:175], v[208:211], v[16:19]
	v_mfma_f32_16x16x32_bf16 v[0:3], v[172:175], v[216:219], v[0:3]
	v_mfma_f32_16x16x32_bf16 v[4:7], v[164:167], v[216:219], v[4:7]
	v_mfma_f32_16x16x32_bf16 v[52:55], v[168:171], v[184:187], v[52:55]
	v_mfma_f32_16x16x32_bf16 v[48:51], v[176:179], v[184:187], v[48:51]
	v_mfma_f32_16x16x32_bf16 v[32:35], v[176:179], v[204:207], v[32:35]
	v_mfma_f32_16x16x32_bf16 v[36:39], v[168:171], v[204:207], v[36:39]
	v_mfma_f32_16x16x32_bf16 v[20:23], v[168:171], v[212:215], v[20:23]
	v_mfma_f32_16x16x32_bf16 v[16:19], v[176:179], v[212:215], v[16:19]
	v_mfma_f32_16x16x32_bf16 v[0:3], v[176:179], v[220:223], v[0:3]
	v_mfma_f32_16x16x32_bf16 v[4:7], v[168:171], v[220:223], v[4:7]
	s_setprio 0
	s_barrier
	s_add_i32 s63, s63, 2
	s_add_u32 s22, s22, 0x100
	s_addc_u32 s23, s23, 0
	s_add_u32 s41, s41, 0x100
	s_addc_u32 s62, s62, 0
	s_cmp_gt_u32 s63, 13
	s_cbranch_scc0 .LBB0_643
	s_and_b64 vcc, exec, s[34:35]
	s_cbranch_vccz .LBB0_646
	s_barrier

.LBB0_966:
	ds_read_b128 v[128:131], v189
	ds_read_b128 v[132:135], v189 offset:1024
	ds_read_b128 v[136:139], v189 offset:2048
	ds_read_b128 v[140:143], v189 offset:3072
	ds_read_b128 v[144:147], v190
	ds_read_b128 v[148:151], v190 offset:1024
	ds_read_b128 v[168:171], v190 offset:2048
	ds_read_b128 v[172:175], v190 offset:3072
	s_add_u32 s4, s22, 0xfffc0080
	s_addc_u32 s5, s23, -1
	s_cmp_eq_u32 s58, 12
	s_cselect_b32 s43, s35, s5
	s_cselect_b32 s42, s41, s4
	s_cselect_b32 s5, s31, s57
	s_cselect_b32 s4, s55, s56
	v_lshl_add_u64 v[184:185], s[22:23], 0, v[160:161]
	s_add_i32 m0, s46, 0xc000
	ds_read_b128 v[176:179], v191
	ds_read_b128 v[180:183], v191 offset:1024
	ds_read_b128 v[192:195], v191 offset:2048
	ds_read_b128 v[198:201], v191 offset:3072
	ds_read_b128 v[204:207], v191 offset:4096
	ds_read_b128 v[208:211], v191 offset:5120
	ds_read_b128 v[212:215], v191 offset:6144
	ds_read_b128 v[216:219], v191 offset:7168
	global_load_lds_dwordx4 v[184:185], off
	v_lshl_add_u64 v[184:185], s[22:23], 0, v[162:163]
	s_add_i32 m0, s46, 0xe000
	s_nop 0
	global_load_lds_dwordx4 v[184:185], off
	s_waitcnt vmcnt(8)
	s_waitcnt lgkmcnt(0)
	s_barrier
	s_setprio 1
	s_waitcnt lgkmcnt(0)
	v_mfma_f32_16x16x32_bf16 v[124:127], v[128:131], v[176:179], v[124:127]
	v_mfma_f32_16x16x32_bf16 v[120:123], v[136:139], v[176:179], v[120:123]
	v_mfma_f32_16x16x32_bf16 v[104:107], v[136:139], v[192:195], v[104:107]
	v_mfma_f32_16x16x32_bf16 v[108:111], v[128:131], v[192:195], v[108:111]
	v_mfma_f32_16x16x32_bf16 v[92:95], v[128:131], v[204:207], v[92:95]
	v_mfma_f32_16x16x32_bf16 v[88:91], v[136:139], v[204:207], v[88:91]
	v_mfma_f32_16x16x32_bf16 v[72:75], v[136:139], v[212:215], v[72:75]
	v_mfma_f32_16x16x32_bf16 v[76:79], v[128:131], v[212:215], v[76:79]
	v_mfma_f32_16x16x32_bf16 v[124:127], v[132:135], v[180:183], v[124:127]
	v_mfma_f32_16x16x32_bf16 v[120:123], v[140:143], v[180:183], v[120:123]
	v_mfma_f32_16x16x32_bf16 v[104:107], v[140:143], v[198:201], v[104:107]
	v_mfma_f32_16x16x32_bf16 v[108:111], v[132:135], v[198:201], v[108:111]
	v_mfma_f32_16x16x32_bf16 v[92:95], v[132:135], v[208:211], v[92:95]
	v_mfma_f32_16x16x32_bf16 v[88:91], v[140:143], v[208:211], v[88:91]
	v_mfma_f32_16x16x32_bf16 v[72:75], v[140:143], v[216:219], v[72:75]
	v_mfma_f32_16x16x32_bf16 v[76:79], v[132:135], v[216:219], v[76:79]
	s_setprio 0
	s_setprio 1
	v_mfma_f32_16x16x32_bf16 v[116:119], v[144:147], v[176:179], v[116:119]
	v_mfma_f32_16x16x32_bf16 v[112:115], v[168:171], v[176:179], v[112:115]
	v_mfma_f32_16x16x32_bf16 v[96:99], v[168:171], v[192:195], v[96:99]
	v_mfma_f32_16x16x32_bf16 v[100:103], v[144:147], v[192:195], v[100:103]
	v_mfma_f32_16x16x32_bf16 v[84:87], v[144:147], v[204:207], v[84:87]
	v_mfma_f32_16x16x32_bf16 v[80:83], v[168:171], v[204:207], v[80:83]
	v_mfma_f32_16x16x32_bf16 v[64:67], v[168:171], v[212:215], v[64:67]
	v_mfma_f32_16x16x32_bf16 v[68:71], v[144:147], v[212:215], v[68:71]
	v_mfma_f32_16x16x32_bf16 v[116:119], v[148:151], v[180:183], v[116:119]
	v_mfma_f32_16x16x32_bf16 v[112:115], v[172:175], v[180:183], v[112:115]
	v_mfma_f32_16x16x32_bf16 v[96:99], v[172:175], v[198:201], v[96:99]
	v_mfma_f32_16x16x32_bf16 v[100:103], v[148:151], v[198:201], v[100:103]
	v_mfma_f32_16x16x32_bf16 v[84:87], v[148:151], v[208:211], v[84:87]
	v_mfma_f32_16x16x32_bf16 v[80:83], v[172:175], v[208:211], v[80:83]
	v_mfma_f32_16x16x32_bf16 v[64:67], v[172:175], v[216:219], v[64:67]
	v_mfma_f32_16x16x32_bf16 v[68:71], v[148:151], v[216:219], v[68:71]
	s_setprio 0
	s_barrier
	s_add_i32 s59, s52, s45
	v_lshl_add_u64 v[184:185], s[4:5], 0, v[154:155]
	s_mov_b32 m0, s59
	ds_read_b128 v[176:179], v191 offset:16384
	ds_read_b128 v[180:183], v191 offset:17408
	ds_read_b128 v[192:195], v191 offset:18432
	ds_read_b128 v[198:201], v191 offset:19456
	ds_read_b128 v[204:207], v191 offset:20480
	ds_read_b128 v[208:211], v191 offset:21504
	ds_read_b128 v[212:215], v191 offset:22528
	ds_read_b128 v[216:219], v191 offset:23552
	global_load_lds_dwordx4 v[184:185], off
	s_add_i32 m0, s59, 0x2000
	s_add_u32 s60, s4, 0x40000
	v_lshl_add_u64 v[220:221], s[4:5], 0, v[158:159]
	s_addc_u32 s61, s5, 0
	s_add_i32 s59, s53, s45
	global_load_lds_dwordx4 v[220:221], off
	v_lshl_add_u64 v[222:223], s[60:61], 0, v[154:155]
	s_mov_b32 m0, s59
	v_lshl_add_u64 v[224:225], s[42:43], 0, v[156:157]
	global_load_lds_dwordx4 v[222:223], off
	v_lshl_add_u64 v[222:223], s[60:61], 0, v[158:159]
	s_add_i32 m0, s59, 0x2000
	s_nop 0
	global_load_lds_dwordx4 v[222:223], off
	v_lshl_add_u64 v[222:223], s[42:43], 0, v[152:153]
	s_mov_b32 m0, s46
	s_nop 0
	global_load_lds_dwordx4 v[222:223], off
	s_mov_b32 m0, s33
	s_nop 0
	global_load_lds_dwordx4 v[224:225], off
	s_waitcnt vmcnt(8)
	s_waitcnt lgkmcnt(0)
	s_barrier
	s_setprio 1
	s_waitcnt lgkmcnt(0)
	v_mfma_f32_16x16x32_bf16 v[60:63], v[128:131], v[176:179], v[60:63]
	v_mfma_f32_16x16x32_bf16 v[56:59], v[136:139], v[176:179], v[56:59]
	v_mfma_f32_16x16x32_bf16 v[40:43], v[136:139], v[192:195], v[40:43]
	v_mfma_f32_16x16x32_bf16 v[44:47], v[128:131], v[192:195], v[44:47]
	v_mfma_f32_16x16x32_bf16 v[28:31], v[128:131], v[204:207], v[28:31]
	v_mfma_f32_16x16x32_bf16 v[24:27], v[136:139], v[204:207], v[24:27]
	v_mfma_f32_16x16x32_bf16 v[8:11], v[136:139], v[212:215], v[8:11]
	v_mfma_f32_16x16x32_bf16 v[12:15], v[128:131], v[212:215], v[12:15]
	v_mfma_f32_16x16x32_bf16 v[60:63], v[132:135], v[180:183], v[60:63]
	v_mfma_f32_16x16x32_bf16 v[56:59], v[140:143], v[180:183], v[56:59]
	v_mfma_f32_16x16x32_bf16 v[40:43], v[140:143], v[198:201], v[40:43]
	v_mfma_f32_16x16x32_bf16 v[44:47], v[132:135], v[198:201], v[44:47]
	v_mfma_f32_16x16x32_bf16 v[28:31], v[132:135], v[208:211], v[28:31]
	v_mfma_f32_16x16x32_bf16 v[24:27], v[140:143], v[208:211], v[24:27]
	v_mfma_f32_16x16x32_bf16 v[8:11], v[140:143], v[216:219], v[8:11]
	v_mfma_f32_16x16x32_bf16 v[12:15], v[132:135], v[216:219], v[12:15]
	s_setprio 0
	s_setprio 1
	v_mfma_f32_16x16x32_bf16 v[52:55], v[144:147], v[176:179], v[52:55]
	v_mfma_f32_16x16x32_bf16 v[48:51], v[168:171], v[176:179], v[48:51]
	v_mfma_f32_16x16x32_bf16 v[32:35], v[168:171], v[192:195], v[32:35]
	v_mfma_f32_16x16x32_bf16 v[36:39], v[144:147], v[192:195], v[36:39]
	v_mfma_f32_16x16x32_bf16 v[20:23], v[144:147], v[204:207], v[20:23]
	v_mfma_f32_16x16x32_bf16 v[16:19], v[168:171], v[204:207], v[16:19]
	v_mfma_f32_16x16x32_bf16 v[0:3], v[168:171], v[212:215], v[0:3]
	v_mfma_f32_16x16x32_bf16 v[4:7], v[144:147], v[212:215], v[4:7]
	v_mfma_f32_16x16x32_bf16 v[52:55], v[148:151], v[180:183], v[52:55]
	v_mfma_f32_16x16x32_bf16 v[48:51], v[172:175], v[180:183], v[48:51]
	v_mfma_f32_16x16x32_bf16 v[32:35], v[172:175], v[198:201], v[32:35]
	v_mfma_f32_16x16x32_bf16 v[36:39], v[148:151], v[198:201], v[36:39]
	v_mfma_f32_16x16x32_bf16 v[20:23], v[148:151], v[208:211], v[20:23]
	v_mfma_f32_16x16x32_bf16 v[16:19], v[172:175], v[208:211], v[16:19]
	v_mfma_f32_16x16x32_bf16 v[0:3], v[172:175], v[216:219], v[0:3]
	v_mfma_f32_16x16x32_bf16 v[4:7], v[148:151], v[216:219], v[4:7]
	s_setprio 0
	s_barrier
	s_add_i32 s59, 0, 0x18000
	s_add_i32 s60, 0, 0x1c000
	v_add_u32_e32 v140, s59, v187
	v_add_u32_e32 v172, s60, v187
	ds_read_b128 v[128:131], v140
	ds_read_b128 v[132:135], v140 offset:1024
	ds_read_b128 v[136:139], v140 offset:2048
	ds_read_b128 v[140:143], v140 offset:3072
	ds_read_b128 v[144:147], v172
	ds_read_b128 v[148:151], v172 offset:1024
	ds_read_b128 v[168:171], v172 offset:2048
	ds_read_b128 v[172:175], v172 offset:3072
	s_add_u32 s42, s42, 0x40000
	s_addc_u32 s43, s43, 0
	s_mov_b32 m0, s47
	v_lshl_add_u64 v[226:227], s[42:43], 0, v[152:153]
	ds_read_b128 v[176:179], v191 offset:32768
	ds_read_b128 v[180:183], v191 offset:33792
	ds_read_b128 v[192:195], v191 offset:34816
	ds_read_b128 v[198:201], v191 offset:35840
	ds_read_b128 v[204:207], v191 offset:36864
	ds_read_b128 v[208:211], v191 offset:37888
	ds_read_b128 v[212:215], v191 offset:38912
	ds_read_b128 v[216:219], v191 offset:39936
	global_load_lds_dwordx4 v[226:227], off
	v_lshl_add_u64 v[226:227], s[42:43], 0, v[156:157]
	s_mov_b32 m0, s48
	s_nop 0
	global_load_lds_dwordx4 v[226:227], off
	s_waitcnt vmcnt(8)
	s_waitcnt lgkmcnt(0)
	s_barrier
	s_setprio 1
	s_waitcnt lgkmcnt(0)
	v_mfma_f32_16x16x32_bf16 v[124:127], v[128:131], v[176:179], v[124:127]
	v_mfma_f32_16x16x32_bf16 v[120:123], v[136:139], v[176:179], v[120:123]
	v_mfma_f32_16x16x32_bf16 v[104:107], v[136:139], v[192:195], v[104:107]
	v_mfma_f32_16x16x32_bf16 v[108:111], v[128:131], v[192:195], v[108:111]
	v_mfma_f32_16x16x32_bf16 v[92:95], v[128:131], v[204:207], v[92:95]
	v_mfma_f32_16x16x32_bf16 v[88:91], v[136:139], v[204:207], v[88:91]
	v_mfma_f32_16x16x32_bf16 v[72:75], v[136:139], v[212:215], v[72:75]
	v_mfma_f32_16x16x32_bf16 v[76:79], v[128:131], v[212:215], v[76:79]
	v_mfma_f32_16x16x32_bf16 v[124:127], v[132:135], v[180:183], v[124:127]
	v_mfma_f32_16x16x32_bf16 v[120:123], v[140:143], v[180:183], v[120:123]
	v_mfma_f32_16x16x32_bf16 v[104:107], v[140:143], v[198:201], v[104:107]
	v_mfma_f32_16x16x32_bf16 v[108:111], v[132:135], v[198:201], v[108:111]
	v_mfma_f32_16x16x32_bf16 v[92:95], v[132:135], v[208:211], v[92:95]
	v_mfma_f32_16x16x32_bf16 v[88:91], v[140:143], v[208:211], v[88:91]
	v_mfma_f32_16x16x32_bf16 v[72:75], v[140:143], v[216:219], v[72:75]
	v_mfma_f32_16x16x32_bf16 v[76:79], v[132:135], v[216:219], v[76:79]
	s_setprio 0
	s_setprio 1
	v_mfma_f32_16x16x32_bf16 v[116:119], v[144:147], v[176:179], v[116:119]
	v_mfma_f32_16x16x32_bf16 v[112:115], v[168:171], v[176:179], v[112:115]
	v_mfma_f32_16x16x32_bf16 v[96:99], v[168:171], v[192:195], v[96:99]
	v_mfma_f32_16x16x32_bf16 v[100:103], v[144:147], v[192:195], v[100:103]
	v_mfma_f32_16x16x32_bf16 v[84:87], v[144:147], v[204:207], v[84:87]
	v_mfma_f32_16x16x32_bf16 v[80:83], v[168:171], v[204:207], v[80:83]
	v_mfma_f32_16x16x32_bf16 v[64:67], v[168:171], v[212:215], v[64:67]
	v_mfma_f32_16x16x32_bf16 v[68:71], v[144:147], v[212:215], v[68:71]
	v_mfma_f32_16x16x32_bf16 v[116:119], v[148:151], v[180:183], v[116:119]
	v_mfma_f32_16x16x32_bf16 v[112:115], v[172:175], v[180:183], v[112:115]
	v_mfma_f32_16x16x32_bf16 v[96:99], v[172:175], v[198:201], v[96:99]
	v_mfma_f32_16x16x32_bf16 v[100:103], v[148:151], v[198:201], v[100:103]
	v_mfma_f32_16x16x32_bf16 v[84:87], v[148:151], v[208:211], v[84:87]
	v_mfma_f32_16x16x32_bf16 v[80:83], v[172:175], v[208:211], v[80:83]
	v_mfma_f32_16x16x32_bf16 v[64:67], v[172:175], v[216:219], v[64:67]
	v_mfma_f32_16x16x32_bf16 v[68:71], v[148:151], v[216:219], v[68:71]
	s_setprio 0
	s_barrier
	s_add_i32 s42, s59, s45
	v_lshl_add_u64 v[184:185], v[184:185], 0, s[26:27]
	s_mov_b32 m0, s42
	ds_read_b128 v[176:179], v191 offset:49152
	ds_read_b128 v[180:183], v191 offset:50176
	ds_read_b128 v[192:195], v191 offset:51200
	ds_read_b128 v[198:201], v191 offset:52224
	ds_read_b128 v[204:207], v191 offset:53248
	ds_read_b128 v[208:211], v191 offset:54272
	ds_read_b128 v[212:215], v191 offset:55296
	ds_read_b128 v[216:219], v191 offset:56320
	global_load_lds_dwordx4 v[184:185], off
	s_add_i32 m0, s42, 0x2000
	s_add_u32 s4, s4, 0x40080
	v_lshl_add_u64 v[184:185], v[220:221], 0, s[26:27]
	s_addc_u32 s5, s5, 0
	s_add_i32 s42, s60, s45
	global_load_lds_dwordx4 v[184:185], off
	v_lshl_add_u64 v[184:185], s[4:5], 0, v[154:155]
	s_mov_b32 m0, s42
	s_nop 0
	global_load_lds_dwordx4 v[184:185], off
	v_lshl_add_u64 v[184:185], s[4:5], 0, v[158:159]
	s_add_i32 m0, s42, 0x2000
	s_nop 0
	global_load_lds_dwordx4 v[184:185], off
	v_lshl_add_u64 v[184:185], v[222:223], 0, s[26:27]
	s_mov_b32 m0, s50
	s_nop 0
	global_load_lds_dwordx4 v[184:185], off
	v_lshl_add_u64 v[184:185], v[224:225], 0, s[26:27]
	s_mov_b32 m0, s51
	s_nop 0
	global_load_lds_dwordx4 v[184:185], off
	s_waitcnt vmcnt(8)
	s_waitcnt lgkmcnt(0)
	s_barrier
	s_setprio 1
	s_waitcnt lgkmcnt(0)
	v_mfma_f32_16x16x32_bf16 v[60:63], v[128:131], v[176:179], v[60:63]
	v_mfma_f32_16x16x32_bf16 v[56:59], v[136:139], v[176:179], v[56:59]
	v_mfma_f32_16x16x32_bf16 v[40:43], v[136:139], v[192:195], v[40:43]
	v_mfma_f32_16x16x32_bf16 v[44:47], v[128:131], v[192:195], v[44:47]
	v_mfma_f32_16x16x32_bf16 v[28:31], v[128:131], v[204:207], v[28:31]
	v_mfma_f32_16x16x32_bf16 v[24:27], v[136:139], v[204:207], v[24:27]
	v_mfma_f32_16x16x32_bf16 v[8:11], v[136:139], v[212:215], v[8:11]
	v_mfma_f32_16x16x32_bf16 v[12:15], v[128:131], v[212:215], v[12:15]
	v_mfma_f32_16x16x32_bf16 v[60:63], v[132:135], v[180:183], v[60:63]
	v_mfma_f32_16x16x32_bf16 v[56:59], v[140:143], v[180:183], v[56:59]
	v_mfma_f32_16x16x32_bf16 v[40:43], v[140:143], v[198:201], v[40:43]
	v_mfma_f32_16x16x32_bf16 v[44:47], v[132:135], v[198:201], v[44:47]
	v_mfma_f32_16x16x32_bf16 v[28:31], v[132:135], v[208:211], v[28:31]
	v_mfma_f32_16x16x32_bf16 v[24:27], v[140:143], v[208:211], v[24:27]
	v_mfma_f32_16x16x32_bf16 v[8:11], v[140:143], v[216:219], v[8:11]
	v_mfma_f32_16x16x32_bf16 v[12:15], v[132:135], v[216:219], v[12:15]
	s_setprio 0
	s_setprio 1
	v_mfma_f32_16x16x32_bf16 v[52:55], v[144:147], v[176:179], v[52:55]
	v_mfma_f32_16x16x32_bf16 v[48:51], v[168:171], v[176:179], v[48:51]
	v_mfma_f32_16x16x32_bf16 v[32:35], v[168:171], v[192:195], v[32:35]
	v_mfma_f32_16x16x32_bf16 v[36:39], v[144:147], v[192:195], v[36:39]
	v_mfma_f32_16x16x32_bf16 v[20:23], v[144:147], v[204:207], v[20:23]
	v_mfma_f32_16x16x32_bf16 v[16:19], v[168:171], v[204:207], v[16:19]
	v_mfma_f32_16x16x32_bf16 v[0:3], v[168:171], v[212:215], v[0:3]
	v_mfma_f32_16x16x32_bf16 v[4:7], v[144:147], v[212:215], v[4:7]
	v_mfma_f32_16x16x32_bf16 v[52:55], v[148:151], v[180:183], v[52:55]
	v_mfma_f32_16x16x32_bf16 v[48:51], v[172:175], v[180:183], v[48:51]
	v_mfma_f32_16x16x32_bf16 v[32:35], v[172:175], v[198:201], v[32:35]
	v_mfma_f32_16x16x32_bf16 v[36:39], v[148:151], v[198:201], v[36:39]
	v_mfma_f32_16x16x32_bf16 v[20:23], v[148:151], v[208:211], v[20:23]
	v_mfma_f32_16x16x32_bf16 v[16:19], v[172:175], v[208:211], v[16:19]
	v_mfma_f32_16x16x32_bf16 v[0:3], v[172:175], v[216:219], v[0:3]
	v_mfma_f32_16x16x32_bf16 v[4:7], v[148:151], v[216:219], v[4:7]
	s_setprio 0
	s_barrier
	s_add_i32 s58, s58, 2
	s_add_u32 s22, s22, 0x100
	s_addc_u32 s23, s23, 0
	s_add_u32 s56, s56, 0x100
	s_addc_u32 s57, s57, 0
	s_cmp_gt_u32 s58, 13
	s_cbranch_scc0 .LBB0_966
	s_and_b64 vcc, exec, s[28:29]
	s_cbranch_vccz .LBB0_969
	s_barrier

.LBB0_1048:
	ds_read_b128 v[146:149], v169
	ds_read_b128 v[150:153], v169 offset:1024
	ds_read_b128 v[154:157], v169 offset:2048
	ds_read_b128 v[160:163], v169 offset:3072
	ds_read_b128 v[178:181], v171
	ds_read_b128 v[182:185], v171 offset:1024
	ds_read_b128 v[186:189], v171 offset:2048
	ds_read_b128 v[190:193], v171 offset:3072
	s_add_u32 s4, s10, 0xfffc0080
	s_addc_u32 s5, s11, -1
	s_cmp_eq_u32 s55, 12
	s_cselect_b32 s13, s9, s5
	s_cselect_b32 s12, s31, s4
	s_cselect_b32 s5, s29, s54
	s_cselect_b32 s4, s52, s53
	v_lshl_add_u64 v[194:195], s[10:11], 0, v[138:139]
	s_add_i32 m0, s41, 0xc000
	ds_read_b128 v[198:201], v173
	ds_read_b128 v[204:207], v173 offset:1024
	ds_read_b128 v[208:211], v173 offset:2048
	ds_read_b128 v[212:215], v173 offset:3072
	ds_read_b128 v[216:219], v173 offset:4096
	ds_read_b128 v[220:223], v173 offset:5120
	ds_read_b128 v[224:227], v173 offset:6144
	ds_read_b128 v[228:231], v173 offset:7168
	global_load_lds_dwordx4 v[194:195], off
	v_lshl_add_u64 v[194:195], s[10:11], 0, v[140:141]
	s_add_i32 m0, s41, 0xe000
	s_nop 0
	global_load_lds_dwordx4 v[194:195], off
	s_waitcnt vmcnt(8)
	s_waitcnt lgkmcnt(0)
	s_barrier
	s_setprio 1
	s_waitcnt lgkmcnt(0)
	v_mfma_f32_16x16x32_bf16 v[124:127], v[146:149], v[198:201], v[124:127]
	v_mfma_f32_16x16x32_bf16 v[116:119], v[154:157], v[198:201], v[116:119]
	v_mfma_f32_16x16x32_bf16 v[100:103], v[154:157], v[208:211], v[100:103]
	v_mfma_f32_16x16x32_bf16 v[108:111], v[146:149], v[208:211], v[108:111]
	v_mfma_f32_16x16x32_bf16 v[92:95], v[146:149], v[216:219], v[92:95]
	v_mfma_f32_16x16x32_bf16 v[84:87], v[154:157], v[216:219], v[84:87]
	v_mfma_f32_16x16x32_bf16 v[68:71], v[154:157], v[224:227], v[68:71]
	v_mfma_f32_16x16x32_bf16 v[76:79], v[146:149], v[224:227], v[76:79]
	v_mfma_f32_16x16x32_bf16 v[124:127], v[150:153], v[204:207], v[124:127]
	v_mfma_f32_16x16x32_bf16 v[116:119], v[160:163], v[204:207], v[116:119]
	v_mfma_f32_16x16x32_bf16 v[100:103], v[160:163], v[212:215], v[100:103]
	v_mfma_f32_16x16x32_bf16 v[108:111], v[150:153], v[212:215], v[108:111]
	v_mfma_f32_16x16x32_bf16 v[92:95], v[150:153], v[220:223], v[92:95]
	v_mfma_f32_16x16x32_bf16 v[84:87], v[160:163], v[220:223], v[84:87]
	v_mfma_f32_16x16x32_bf16 v[68:71], v[160:163], v[228:231], v[68:71]
	v_mfma_f32_16x16x32_bf16 v[76:79], v[150:153], v[228:231], v[76:79]
	s_setprio 0
	s_setprio 1
	v_mfma_f32_16x16x32_bf16 v[120:123], v[178:181], v[198:201], v[120:123]
	v_mfma_f32_16x16x32_bf16 v[112:115], v[186:189], v[198:201], v[112:115]
	v_mfma_f32_16x16x32_bf16 v[96:99], v[186:189], v[208:211], v[96:99]
	v_mfma_f32_16x16x32_bf16 v[104:107], v[178:181], v[208:211], v[104:107]
	v_mfma_f32_16x16x32_bf16 v[88:91], v[178:181], v[216:219], v[88:91]
	v_mfma_f32_16x16x32_bf16 v[80:83], v[186:189], v[216:219], v[80:83]
	v_mfma_f32_16x16x32_bf16 v[64:67], v[186:189], v[224:227], v[64:67]
	v_mfma_f32_16x16x32_bf16 v[72:75], v[178:181], v[224:227], v[72:75]
	v_mfma_f32_16x16x32_bf16 v[120:123], v[182:185], v[204:207], v[120:123]
	v_mfma_f32_16x16x32_bf16 v[112:115], v[190:193], v[204:207], v[112:115]
	v_mfma_f32_16x16x32_bf16 v[96:99], v[190:193], v[212:215], v[96:99]
	v_mfma_f32_16x16x32_bf16 v[104:107], v[182:185], v[212:215], v[104:107]
	v_mfma_f32_16x16x32_bf16 v[88:91], v[182:185], v[220:223], v[88:91]
	v_mfma_f32_16x16x32_bf16 v[80:83], v[190:193], v[220:223], v[80:83]
	v_mfma_f32_16x16x32_bf16 v[64:67], v[190:193], v[228:231], v[64:67]
	v_mfma_f32_16x16x32_bf16 v[72:75], v[182:185], v[228:231], v[72:75]
	s_setprio 0
	s_barrier
	s_add_i32 s56, s48, s39
	v_lshl_add_u64 v[194:195], s[4:5], 0, v[132:133]
	s_mov_b32 m0, s56
	ds_read_b128 v[198:201], v173 offset:16384
	ds_read_b128 v[204:207], v173 offset:17408
	ds_read_b128 v[208:211], v173 offset:18432
	ds_read_b128 v[212:215], v173 offset:19456
	ds_read_b128 v[216:219], v173 offset:20480
	ds_read_b128 v[220:223], v173 offset:21504
	ds_read_b128 v[224:227], v173 offset:22528
	ds_read_b128 v[228:231], v173 offset:23552
	global_load_lds_dwordx4 v[194:195], off
	s_add_i32 m0, s56, 0x2000
	s_add_u32 s56, s4, 0x40000
	v_lshl_add_u64 v[232:233], s[4:5], 0, v[128:129]
	s_addc_u32 s57, s5, 0
	s_add_i32 s58, s49, s39
	global_load_lds_dwordx4 v[232:233], off
	v_lshl_add_u64 v[234:235], s[56:57], 0, v[132:133]
	s_mov_b32 m0, s58
	v_lshl_add_u64 v[236:237], s[12:13], 0, v[130:131]
	global_load_lds_dwordx4 v[234:235], off
	v_lshl_add_u64 v[234:235], s[56:57], 0, v[128:129]
	s_add_i32 m0, s58, 0x2000
	s_nop 0
	global_load_lds_dwordx4 v[234:235], off
	v_lshl_add_u64 v[234:235], s[12:13], 0, v[134:135]
	s_mov_b32 m0, s41
	s_nop 0
	global_load_lds_dwordx4 v[234:235], off
	s_mov_b32 m0, s42
	s_nop 0
	global_load_lds_dwordx4 v[236:237], off
	s_waitcnt vmcnt(8)
	s_waitcnt lgkmcnt(0)
	s_barrier
	s_setprio 1
	s_waitcnt lgkmcnt(0)
	v_mfma_f32_16x16x32_bf16 v[60:63], v[146:149], v[198:201], v[60:63]
	v_mfma_f32_16x16x32_bf16 v[52:55], v[154:157], v[198:201], v[52:55]
	v_mfma_f32_16x16x32_bf16 v[36:39], v[154:157], v[208:211], v[36:39]
	v_mfma_f32_16x16x32_bf16 v[44:47], v[146:149], v[208:211], v[44:47]
	v_mfma_f32_16x16x32_bf16 v[28:31], v[146:149], v[216:219], v[28:31]
	v_mfma_f32_16x16x32_bf16 v[20:23], v[154:157], v[216:219], v[20:23]
	v_mfma_f32_16x16x32_bf16 v[4:7], v[154:157], v[224:227], v[4:7]
	v_mfma_f32_16x16x32_bf16 v[12:15], v[146:149], v[224:227], v[12:15]
	v_mfma_f32_16x16x32_bf16 v[60:63], v[150:153], v[204:207], v[60:63]
	v_mfma_f32_16x16x32_bf16 v[52:55], v[160:163], v[204:207], v[52:55]
	v_mfma_f32_16x16x32_bf16 v[36:39], v[160:163], v[212:215], v[36:39]
	v_mfma_f32_16x16x32_bf16 v[44:47], v[150:153], v[212:215], v[44:47]
	v_mfma_f32_16x16x32_bf16 v[28:31], v[150:153], v[220:223], v[28:31]
	v_mfma_f32_16x16x32_bf16 v[20:23], v[160:163], v[220:223], v[20:23]
	v_mfma_f32_16x16x32_bf16 v[4:7], v[160:163], v[228:231], v[4:7]
	v_mfma_f32_16x16x32_bf16 v[12:15], v[150:153], v[228:231], v[12:15]
	s_setprio 0
	s_setprio 1
	v_mfma_f32_16x16x32_bf16 v[56:59], v[178:181], v[198:201], v[56:59]
	v_mfma_f32_16x16x32_bf16 v[48:51], v[186:189], v[198:201], v[48:51]
	v_mfma_f32_16x16x32_bf16 v[32:35], v[186:189], v[208:211], v[32:35]
	v_mfma_f32_16x16x32_bf16 v[40:43], v[178:181], v[208:211], v[40:43]
	v_mfma_f32_16x16x32_bf16 v[24:27], v[178:181], v[216:219], v[24:27]
	v_mfma_f32_16x16x32_bf16 v[16:19], v[186:189], v[216:219], v[16:19]
	v_mfma_f32_16x16x32_bf16 v[0:3], v[186:189], v[224:227], v[0:3]
	v_mfma_f32_16x16x32_bf16 v[8:11], v[178:181], v[224:227], v[8:11]
	v_mfma_f32_16x16x32_bf16 v[56:59], v[182:185], v[204:207], v[56:59]
	v_mfma_f32_16x16x32_bf16 v[48:51], v[190:193], v[204:207], v[48:51]
	v_mfma_f32_16x16x32_bf16 v[32:35], v[190:193], v[212:215], v[32:35]
	v_mfma_f32_16x16x32_bf16 v[40:43], v[182:185], v[212:215], v[40:43]
	v_mfma_f32_16x16x32_bf16 v[24:27], v[182:185], v[220:223], v[24:27]
	v_mfma_f32_16x16x32_bf16 v[16:19], v[190:193], v[220:223], v[16:19]
	v_mfma_f32_16x16x32_bf16 v[0:3], v[190:193], v[228:231], v[0:3]
	v_mfma_f32_16x16x32_bf16 v[8:11], v[182:185], v[228:231], v[8:11]
	s_setprio 0
	s_barrier
	s_add_i32 s56, 0, 0x18000
	v_add_u32_e32 v158, s56, v165
	s_add_i32 s57, 0, 0x1c000
	ds_read_b128 v[146:149], v158
	ds_read_b128 v[150:153], v158 offset:1024
	ds_read_b128 v[154:157], v158 offset:2048
	ds_read_b128 v[160:163], v158 offset:3072
	v_add_u32_e32 v158, s57, v165
	ds_read_b128 v[178:181], v158
	ds_read_b128 v[182:185], v158 offset:1024
	ds_read_b128 v[186:189], v158 offset:2048
	ds_read_b128 v[190:193], v158 offset:3072
	s_add_u32 s12, s12, 0x40000
	s_addc_u32 s13, s13, 0
	s_mov_b32 m0, s43
	v_lshl_add_u64 v[238:239], s[12:13], 0, v[134:135]
	ds_read_b128 v[198:201], v173 offset:32768
	ds_read_b128 v[204:207], v173 offset:33792
	ds_read_b128 v[208:211], v173 offset:34816
	ds_read_b128 v[212:215], v173 offset:35840
	ds_read_b128 v[216:219], v173 offset:36864
	ds_read_b128 v[220:223], v173 offset:37888
	ds_read_b128 v[224:227], v173 offset:38912
	ds_read_b128 v[228:231], v173 offset:39936
	global_load_lds_dwordx4 v[238:239], off
	v_lshl_add_u64 v[238:239], s[12:13], 0, v[130:131]
	s_mov_b32 m0, s44
	s_nop 0
	global_load_lds_dwordx4 v[238:239], off
	s_waitcnt vmcnt(8)
	s_waitcnt lgkmcnt(0)
	s_barrier
	s_setprio 1
	s_waitcnt lgkmcnt(0)
	v_mfma_f32_16x16x32_bf16 v[124:127], v[146:149], v[198:201], v[124:127]
	v_mfma_f32_16x16x32_bf16 v[116:119], v[154:157], v[198:201], v[116:119]
	v_mfma_f32_16x16x32_bf16 v[100:103], v[154:157], v[208:211], v[100:103]
	v_mfma_f32_16x16x32_bf16 v[108:111], v[146:149], v[208:211], v[108:111]
	v_mfma_f32_16x16x32_bf16 v[92:95], v[146:149], v[216:219], v[92:95]
	v_mfma_f32_16x16x32_bf16 v[84:87], v[154:157], v[216:219], v[84:87]
	v_mfma_f32_16x16x32_bf16 v[68:71], v[154:157], v[224:227], v[68:71]
	v_mfma_f32_16x16x32_bf16 v[76:79], v[146:149], v[224:227], v[76:79]
	v_mfma_f32_16x16x32_bf16 v[124:127], v[150:153], v[204:207], v[124:127]
	v_mfma_f32_16x16x32_bf16 v[116:119], v[160:163], v[204:207], v[116:119]
	v_mfma_f32_16x16x32_bf16 v[100:103], v[160:163], v[212:215], v[100:103]
	v_mfma_f32_16x16x32_bf16 v[108:111], v[150:153], v[212:215], v[108:111]
	v_mfma_f32_16x16x32_bf16 v[92:95], v[150:153], v[220:223], v[92:95]
	v_mfma_f32_16x16x32_bf16 v[84:87], v[160:163], v[220:223], v[84:87]
	v_mfma_f32_16x16x32_bf16 v[68:71], v[160:163], v[228:231], v[68:71]
	v_mfma_f32_16x16x32_bf16 v[76:79], v[150:153], v[228:231], v[76:79]
	s_setprio 0
	s_setprio 1
	v_mfma_f32_16x16x32_bf16 v[120:123], v[178:181], v[198:201], v[120:123]
	v_mfma_f32_16x16x32_bf16 v[112:115], v[186:189], v[198:201], v[112:115]
	v_mfma_f32_16x16x32_bf16 v[96:99], v[186:189], v[208:211], v[96:99]
	v_mfma_f32_16x16x32_bf16 v[104:107], v[178:181], v[208:211], v[104:107]
	v_mfma_f32_16x16x32_bf16 v[88:91], v[178:181], v[216:219], v[88:91]
	v_mfma_f32_16x16x32_bf16 v[80:83], v[186:189], v[216:219], v[80:83]
	v_mfma_f32_16x16x32_bf16 v[64:67], v[186:189], v[224:227], v[64:67]
	v_mfma_f32_16x16x32_bf16 v[72:75], v[178:181], v[224:227], v[72:75]
	v_mfma_f32_16x16x32_bf16 v[120:123], v[182:185], v[204:207], v[120:123]
	v_mfma_f32_16x16x32_bf16 v[112:115], v[190:193], v[204:207], v[112:115]
	v_mfma_f32_16x16x32_bf16 v[96:99], v[190:193], v[212:215], v[96:99]
	v_mfma_f32_16x16x32_bf16 v[104:107], v[182:185], v[212:215], v[104:107]
	v_mfma_f32_16x16x32_bf16 v[88:91], v[182:185], v[220:223], v[88:91]
	v_mfma_f32_16x16x32_bf16 v[80:83], v[190:193], v[220:223], v[80:83]
	v_mfma_f32_16x16x32_bf16 v[64:67], v[190:193], v[228:231], v[64:67]
	v_mfma_f32_16x16x32_bf16 v[72:75], v[182:185], v[228:231], v[72:75]
	s_setprio 0
	s_barrier
	s_add_i32 s12, s56, s39
	v_lshl_add_u64 v[194:195], v[194:195], 0, s[24:25]
	s_mov_b32 m0, s12
	ds_read_b128 v[198:201], v173 offset:49152
	ds_read_b128 v[204:207], v173 offset:50176
	ds_read_b128 v[208:211], v173 offset:51200
	ds_read_b128 v[212:215], v173 offset:52224
	ds_read_b128 v[216:219], v173 offset:53248
	ds_read_b128 v[220:223], v173 offset:54272
	ds_read_b128 v[224:227], v173 offset:55296
	ds_read_b128 v[228:231], v173 offset:56320
	global_load_lds_dwordx4 v[194:195], off
	s_add_i32 m0, s12, 0x2000
	s_add_u32 s4, s4, 0x40080
	v_lshl_add_u64 v[194:195], v[232:233], 0, s[24:25]
	s_addc_u32 s5, s5, 0
	s_add_i32 s12, s57, s39
	global_load_lds_dwordx4 v[194:195], off
	v_lshl_add_u64 v[194:195], s[4:5], 0, v[132:133]
	s_mov_b32 m0, s12
	s_nop 0
	global_load_lds_dwordx4 v[194:195], off
	v_lshl_add_u64 v[194:195], s[4:5], 0, v[128:129]
	s_add_i32 m0, s12, 0x2000
	s_nop 0
	global_load_lds_dwordx4 v[194:195], off
	v_lshl_add_u64 v[194:195], v[234:235], 0, s[24:25]
	s_mov_b32 m0, s46
	s_nop 0
	global_load_lds_dwordx4 v[194:195], off
	v_lshl_add_u64 v[194:195], v[236:237], 0, s[24:25]
	s_mov_b32 m0, s47
	s_nop 0
	global_load_lds_dwordx4 v[194:195], off
	s_waitcnt vmcnt(8)
	s_waitcnt lgkmcnt(0)
	s_barrier
	s_setprio 1
	s_waitcnt lgkmcnt(0)
	v_mfma_f32_16x16x32_bf16 v[60:63], v[146:149], v[198:201], v[60:63]
	v_mfma_f32_16x16x32_bf16 v[52:55], v[154:157], v[198:201], v[52:55]
	v_mfma_f32_16x16x32_bf16 v[36:39], v[154:157], v[208:211], v[36:39]
	v_mfma_f32_16x16x32_bf16 v[44:47], v[146:149], v[208:211], v[44:47]
	v_mfma_f32_16x16x32_bf16 v[28:31], v[146:149], v[216:219], v[28:31]
	v_mfma_f32_16x16x32_bf16 v[20:23], v[154:157], v[216:219], v[20:23]
	v_mfma_f32_16x16x32_bf16 v[4:7], v[154:157], v[224:227], v[4:7]
	v_mfma_f32_16x16x32_bf16 v[12:15], v[146:149], v[224:227], v[12:15]
	v_mfma_f32_16x16x32_bf16 v[60:63], v[150:153], v[204:207], v[60:63]
	v_mfma_f32_16x16x32_bf16 v[52:55], v[160:163], v[204:207], v[52:55]
	v_mfma_f32_16x16x32_bf16 v[36:39], v[160:163], v[212:215], v[36:39]
	v_mfma_f32_16x16x32_bf16 v[44:47], v[150:153], v[212:215], v[44:47]
	v_mfma_f32_16x16x32_bf16 v[28:31], v[150:153], v[220:223], v[28:31]
	v_mfma_f32_16x16x32_bf16 v[20:23], v[160:163], v[220:223], v[20:23]
	v_mfma_f32_16x16x32_bf16 v[4:7], v[160:163], v[228:231], v[4:7]
	v_mfma_f32_16x16x32_bf16 v[12:15], v[150:153], v[228:231], v[12:15]
	s_setprio 0
	s_setprio 1
	v_mfma_f32_16x16x32_bf16 v[56:59], v[178:181], v[198:201], v[56:59]
	v_mfma_f32_16x16x32_bf16 v[48:51], v[186:189], v[198:201], v[48:51]
	v_mfma_f32_16x16x32_bf16 v[32:35], v[186:189], v[208:211], v[32:35]
	v_mfma_f32_16x16x32_bf16 v[40:43], v[178:181], v[208:211], v[40:43]
	v_mfma_f32_16x16x32_bf16 v[24:27], v[178:181], v[216:219], v[24:27]
	v_mfma_f32_16x16x32_bf16 v[16:19], v[186:189], v[216:219], v[16:19]
	v_mfma_f32_16x16x32_bf16 v[0:3], v[186:189], v[224:227], v[0:3]
	v_mfma_f32_16x16x32_bf16 v[8:11], v[178:181], v[224:227], v[8:11]
	v_mfma_f32_16x16x32_bf16 v[56:59], v[182:185], v[204:207], v[56:59]
	v_mfma_f32_16x16x32_bf16 v[48:51], v[190:193], v[204:207], v[48:51]
	v_mfma_f32_16x16x32_bf16 v[32:35], v[190:193], v[212:215], v[32:35]
	v_mfma_f32_16x16x32_bf16 v[40:43], v[182:185], v[212:215], v[40:43]
	v_mfma_f32_16x16x32_bf16 v[24:27], v[182:185], v[220:223], v[24:27]
	v_mfma_f32_16x16x32_bf16 v[16:19], v[190:193], v[220:223], v[16:19]
	v_mfma_f32_16x16x32_bf16 v[0:3], v[190:193], v[228:231], v[0:3]
	v_mfma_f32_16x16x32_bf16 v[8:11], v[182:185], v[228:231], v[8:11]
	s_setprio 0
	s_barrier
	s_add_i32 s55, s55, 2
	s_add_u32 s10, s10, 0x100
	s_addc_u32 s11, s11, 0
	s_add_u32 s53, s53, 0x100
	s_addc_u32 s54, s54, 0
	s_cmp_gt_u32 s55, 13
	s_cbranch_scc0 .LBB0_1048
	s_and_b64 vcc, exec, s[26:27]
	s_cbranch_vccz .LBB0_1051
	s_barrier

.LBB0_1124:
	ds_read_b128 v[128:131], v189
	ds_read_b128 v[132:135], v189 offset:1024
	ds_read_b128 v[136:139], v189 offset:2048
	ds_read_b128 v[140:143], v189 offset:3072
	ds_read_b128 v[144:147], v190
	ds_read_b128 v[148:151], v190 offset:1024
	ds_read_b128 v[168:171], v190 offset:2048
	ds_read_b128 v[172:175], v190 offset:3072
	s_add_u32 s34, s30, 0x100
	s_addc_u32 s35, s31, 0
	s_cmp_eq_u32 s56, 40
	s_cselect_b32 s39, s9, s35
	s_cselect_b32 s38, s8, s34
	s_cselect_b32 s37, s29, s55
	s_cselect_b32 s36, s28, s54
	v_lshl_add_u64 v[184:185], s[30:31], 0, v[160:161]
	s_add_i32 m0, s42, 0xc000
	ds_read_b128 v[176:179], v191
	ds_read_b128 v[180:183], v191 offset:1024
	ds_read_b128 v[192:195], v191 offset:2048
	ds_read_b128 v[198:201], v191 offset:3072
	ds_read_b128 v[204:207], v191 offset:4096
	ds_read_b128 v[208:211], v191 offset:5120
	ds_read_b128 v[212:215], v191 offset:6144
	ds_read_b128 v[216:219], v191 offset:7168
	global_load_lds_dwordx4 v[184:185], off
	v_lshl_add_u64 v[184:185], s[30:31], 0, v[162:163]
	s_add_i32 m0, s42, 0xe000
	s_nop 0
	global_load_lds_dwordx4 v[184:185], off
	s_waitcnt vmcnt(8)
	s_waitcnt lgkmcnt(0)
	s_barrier
	s_setprio 1
	s_waitcnt lgkmcnt(0)
	v_mfma_f32_16x16x32_bf16 v[124:127], v[128:131], v[176:179], v[124:127]
	v_mfma_f32_16x16x32_bf16 v[120:123], v[136:139], v[176:179], v[120:123]
	v_mfma_f32_16x16x32_bf16 v[104:107], v[136:139], v[192:195], v[104:107]
	v_mfma_f32_16x16x32_bf16 v[108:111], v[128:131], v[192:195], v[108:111]
	v_mfma_f32_16x16x32_bf16 v[92:95], v[128:131], v[204:207], v[92:95]
	v_mfma_f32_16x16x32_bf16 v[88:91], v[136:139], v[204:207], v[88:91]
	v_mfma_f32_16x16x32_bf16 v[72:75], v[136:139], v[212:215], v[72:75]
	v_mfma_f32_16x16x32_bf16 v[76:79], v[128:131], v[212:215], v[76:79]
	v_mfma_f32_16x16x32_bf16 v[124:127], v[132:135], v[180:183], v[124:127]
	v_mfma_f32_16x16x32_bf16 v[120:123], v[140:143], v[180:183], v[120:123]
	v_mfma_f32_16x16x32_bf16 v[104:107], v[140:143], v[198:201], v[104:107]
	v_mfma_f32_16x16x32_bf16 v[108:111], v[132:135], v[198:201], v[108:111]
	v_mfma_f32_16x16x32_bf16 v[92:95], v[132:135], v[208:211], v[92:95]
	v_mfma_f32_16x16x32_bf16 v[88:91], v[140:143], v[208:211], v[88:91]
	v_mfma_f32_16x16x32_bf16 v[72:75], v[140:143], v[216:219], v[72:75]
	v_mfma_f32_16x16x32_bf16 v[76:79], v[132:135], v[216:219], v[76:79]
	s_setprio 0
	s_setprio 1
	v_mfma_f32_16x16x32_bf16 v[116:119], v[144:147], v[176:179], v[116:119]
	v_mfma_f32_16x16x32_bf16 v[112:115], v[168:171], v[176:179], v[112:115]
	v_mfma_f32_16x16x32_bf16 v[96:99], v[168:171], v[192:195], v[96:99]
	v_mfma_f32_16x16x32_bf16 v[100:103], v[144:147], v[192:195], v[100:103]
	v_mfma_f32_16x16x32_bf16 v[84:87], v[144:147], v[204:207], v[84:87]
	v_mfma_f32_16x16x32_bf16 v[80:83], v[168:171], v[204:207], v[80:83]
	v_mfma_f32_16x16x32_bf16 v[64:67], v[168:171], v[212:215], v[64:67]
	v_mfma_f32_16x16x32_bf16 v[68:71], v[144:147], v[212:215], v[68:71]
	v_mfma_f32_16x16x32_bf16 v[116:119], v[148:151], v[180:183], v[116:119]
	v_mfma_f32_16x16x32_bf16 v[112:115], v[172:175], v[180:183], v[112:115]
	v_mfma_f32_16x16x32_bf16 v[96:99], v[172:175], v[198:201], v[96:99]
	v_mfma_f32_16x16x32_bf16 v[100:103], v[148:151], v[198:201], v[100:103]
	v_mfma_f32_16x16x32_bf16 v[84:87], v[148:151], v[208:211], v[84:87]
	v_mfma_f32_16x16x32_bf16 v[80:83], v[172:175], v[208:211], v[80:83]
	v_mfma_f32_16x16x32_bf16 v[64:67], v[172:175], v[216:219], v[64:67]
	v_mfma_f32_16x16x32_bf16 v[68:71], v[148:151], v[216:219], v[68:71]
	s_setprio 0
	s_barrier
	s_add_i32 s30, s48, s41
	v_lshl_add_u64 v[184:185], s[36:37], 0, v[154:155]
	s_mov_b32 m0, s30
	ds_read_b128 v[176:179], v191 offset:16384
	ds_read_b128 v[180:183], v191 offset:17408
	ds_read_b128 v[192:195], v191 offset:18432
	ds_read_b128 v[198:201], v191 offset:19456
	ds_read_b128 v[204:207], v191 offset:20480
	ds_read_b128 v[208:211], v191 offset:21504
	ds_read_b128 v[212:215], v191 offset:22528
	ds_read_b128 v[216:219], v191 offset:23552
	global_load_lds_dwordx4 v[184:185], off
	s_add_i32 m0, s30, 0x2000
	s_add_u32 s30, s36, 0xb0000
	v_lshl_add_u64 v[220:221], s[36:37], 0, v[158:159]
	s_addc_u32 s31, s37, 0
	s_add_i32 s57, s49, s41
	global_load_lds_dwordx4 v[220:221], off
	v_lshl_add_u64 v[222:223], s[30:31], 0, v[154:155]
	s_mov_b32 m0, s57
	v_lshl_add_u64 v[224:225], s[38:39], 0, v[156:157]
	global_load_lds_dwordx4 v[222:223], off
	v_lshl_add_u64 v[222:223], s[30:31], 0, v[158:159]
	s_add_i32 m0, s57, 0x2000
	s_nop 0
	global_load_lds_dwordx4 v[222:223], off
	v_lshl_add_u64 v[222:223], s[38:39], 0, v[152:153]
	s_mov_b32 m0, s42
	s_nop 0
	global_load_lds_dwordx4 v[222:223], off
	s_mov_b32 m0, s33
	s_nop 0
	global_load_lds_dwordx4 v[224:225], off
	s_waitcnt vmcnt(8)
	s_waitcnt lgkmcnt(0)
	s_barrier
	s_setprio 1
	s_waitcnt lgkmcnt(0)
	v_mfma_f32_16x16x32_bf16 v[60:63], v[128:131], v[176:179], v[60:63]
	v_mfma_f32_16x16x32_bf16 v[56:59], v[136:139], v[176:179], v[56:59]
	v_mfma_f32_16x16x32_bf16 v[40:43], v[136:139], v[192:195], v[40:43]
	v_mfma_f32_16x16x32_bf16 v[44:47], v[128:131], v[192:195], v[44:47]
	v_mfma_f32_16x16x32_bf16 v[28:31], v[128:131], v[204:207], v[28:31]
	v_mfma_f32_16x16x32_bf16 v[24:27], v[136:139], v[204:207], v[24:27]
	v_mfma_f32_16x16x32_bf16 v[8:11], v[136:139], v[212:215], v[8:11]
	v_mfma_f32_16x16x32_bf16 v[12:15], v[128:131], v[212:215], v[12:15]
	v_mfma_f32_16x16x32_bf16 v[60:63], v[132:135], v[180:183], v[60:63]
	v_mfma_f32_16x16x32_bf16 v[56:59], v[140:143], v[180:183], v[56:59]
	v_mfma_f32_16x16x32_bf16 v[40:43], v[140:143], v[198:201], v[40:43]
	v_mfma_f32_16x16x32_bf16 v[44:47], v[132:135], v[198:201], v[44:47]
	v_mfma_f32_16x16x32_bf16 v[28:31], v[132:135], v[208:211], v[28:31]
	v_mfma_f32_16x16x32_bf16 v[24:27], v[140:143], v[208:211], v[24:27]
	v_mfma_f32_16x16x32_bf16 v[8:11], v[140:143], v[216:219], v[8:11]
	v_mfma_f32_16x16x32_bf16 v[12:15], v[132:135], v[216:219], v[12:15]
	s_setprio 0
	s_setprio 1
	v_mfma_f32_16x16x32_bf16 v[52:55], v[144:147], v[176:179], v[52:55]
	v_mfma_f32_16x16x32_bf16 v[48:51], v[168:171], v[176:179], v[48:51]
	v_mfma_f32_16x16x32_bf16 v[32:35], v[168:171], v[192:195], v[32:35]
	v_mfma_f32_16x16x32_bf16 v[36:39], v[144:147], v[192:195], v[36:39]
	v_mfma_f32_16x16x32_bf16 v[20:23], v[144:147], v[204:207], v[20:23]
	v_mfma_f32_16x16x32_bf16 v[16:19], v[168:171], v[204:207], v[16:19]
	v_mfma_f32_16x16x32_bf16 v[0:3], v[168:171], v[212:215], v[0:3]
	v_mfma_f32_16x16x32_bf16 v[4:7], v[144:147], v[212:215], v[4:7]
	v_mfma_f32_16x16x32_bf16 v[52:55], v[148:151], v[180:183], v[52:55]
	v_mfma_f32_16x16x32_bf16 v[48:51], v[172:175], v[180:183], v[48:51]
	v_mfma_f32_16x16x32_bf16 v[32:35], v[172:175], v[198:201], v[32:35]
	v_mfma_f32_16x16x32_bf16 v[36:39], v[148:151], v[198:201], v[36:39]
	v_mfma_f32_16x16x32_bf16 v[20:23], v[148:151], v[208:211], v[20:23]
	v_mfma_f32_16x16x32_bf16 v[16:19], v[172:175], v[208:211], v[16:19]
	v_mfma_f32_16x16x32_bf16 v[0:3], v[172:175], v[216:219], v[0:3]
	v_mfma_f32_16x16x32_bf16 v[4:7], v[148:151], v[216:219], v[4:7]
	s_setprio 0
	s_barrier
	s_add_i32 s57, 0, 0x18000
	s_add_i32 s58, 0, 0x1c000
	v_add_u32_e32 v140, s57, v187
	v_add_u32_e32 v172, s58, v187
	ds_read_b128 v[128:131], v140
	ds_read_b128 v[132:135], v140 offset:1024
	ds_read_b128 v[136:139], v140 offset:2048
	ds_read_b128 v[140:143], v140 offset:3072
	ds_read_b128 v[144:147], v172
	ds_read_b128 v[148:151], v172 offset:1024
	ds_read_b128 v[168:171], v172 offset:2048
	ds_read_b128 v[172:175], v172 offset:3072
	s_add_u32 s30, s38, 0xb0000
	s_addc_u32 s31, s39, 0
	s_mov_b32 m0, s43
	v_lshl_add_u64 v[226:227], s[30:31], 0, v[152:153]
	ds_read_b128 v[176:179], v191 offset:32768
	ds_read_b128 v[180:183], v191 offset:33792
	ds_read_b128 v[192:195], v191 offset:34816
	ds_read_b128 v[198:201], v191 offset:35840
	ds_read_b128 v[204:207], v191 offset:36864
	ds_read_b128 v[208:211], v191 offset:37888
	ds_read_b128 v[212:215], v191 offset:38912
	ds_read_b128 v[216:219], v191 offset:39936
	global_load_lds_dwordx4 v[226:227], off
	v_lshl_add_u64 v[226:227], s[30:31], 0, v[156:157]
	s_mov_b32 m0, s44
	s_nop 0
	global_load_lds_dwordx4 v[226:227], off
	s_waitcnt vmcnt(8)
	s_waitcnt lgkmcnt(0)
	s_barrier
	s_setprio 1
	s_waitcnt lgkmcnt(0)
	v_mfma_f32_16x16x32_bf16 v[124:127], v[128:131], v[176:179], v[124:127]
	v_mfma_f32_16x16x32_bf16 v[120:123], v[136:139], v[176:179], v[120:123]
	v_mfma_f32_16x16x32_bf16 v[104:107], v[136:139], v[192:195], v[104:107]
	v_mfma_f32_16x16x32_bf16 v[108:111], v[128:131], v[192:195], v[108:111]
	v_mfma_f32_16x16x32_bf16 v[92:95], v[128:131], v[204:207], v[92:95]
	v_mfma_f32_16x16x32_bf16 v[88:91], v[136:139], v[204:207], v[88:91]
	v_mfma_f32_16x16x32_bf16 v[72:75], v[136:139], v[212:215], v[72:75]
	v_mfma_f32_16x16x32_bf16 v[76:79], v[128:131], v[212:215], v[76:79]
	v_mfma_f32_16x16x32_bf16 v[124:127], v[132:135], v[180:183], v[124:127]
	v_mfma_f32_16x16x32_bf16 v[120:123], v[140:143], v[180:183], v[120:123]
	v_mfma_f32_16x16x32_bf16 v[104:107], v[140:143], v[198:201], v[104:107]
	v_mfma_f32_16x16x32_bf16 v[108:111], v[132:135], v[198:201], v[108:111]
	v_mfma_f32_16x16x32_bf16 v[92:95], v[132:135], v[208:211], v[92:95]
	v_mfma_f32_16x16x32_bf16 v[88:91], v[140:143], v[208:211], v[88:91]
	v_mfma_f32_16x16x32_bf16 v[72:75], v[140:143], v[216:219], v[72:75]
	v_mfma_f32_16x16x32_bf16 v[76:79], v[132:135], v[216:219], v[76:79]
	s_setprio 0
	s_setprio 1
	v_mfma_f32_16x16x32_bf16 v[116:119], v[144:147], v[176:179], v[116:119]
	v_mfma_f32_16x16x32_bf16 v[112:115], v[168:171], v[176:179], v[112:115]
	v_mfma_f32_16x16x32_bf16 v[96:99], v[168:171], v[192:195], v[96:99]
	v_mfma_f32_16x16x32_bf16 v[100:103], v[144:147], v[192:195], v[100:103]
	v_mfma_f32_16x16x32_bf16 v[84:87], v[144:147], v[204:207], v[84:87]
	v_mfma_f32_16x16x32_bf16 v[80:83], v[168:171], v[204:207], v[80:83]
	v_mfma_f32_16x16x32_bf16 v[64:67], v[168:171], v[212:215], v[64:67]
	v_mfma_f32_16x16x32_bf16 v[68:71], v[144:147], v[212:215], v[68:71]
	v_mfma_f32_16x16x32_bf16 v[116:119], v[148:151], v[180:183], v[116:119]
	v_mfma_f32_16x16x32_bf16 v[112:115], v[172:175], v[180:183], v[112:115]
	v_mfma_f32_16x16x32_bf16 v[96:99], v[172:175], v[198:201], v[96:99]
	v_mfma_f32_16x16x32_bf16 v[100:103], v[148:151], v[198:201], v[100:103]
	v_mfma_f32_16x16x32_bf16 v[84:87], v[148:151], v[208:211], v[84:87]
	v_mfma_f32_16x16x32_bf16 v[80:83], v[172:175], v[208:211], v[80:83]
	v_mfma_f32_16x16x32_bf16 v[64:67], v[172:175], v[216:219], v[64:67]
	v_mfma_f32_16x16x32_bf16 v[68:71], v[148:151], v[216:219], v[68:71]
	s_setprio 0
	s_barrier
	s_add_i32 s30, s57, s41
	v_lshl_add_u64 v[184:185], v[184:185], 0, s[24:25]
	s_mov_b32 m0, s30
	ds_read_b128 v[176:179], v191 offset:49152
	ds_read_b128 v[180:183], v191 offset:50176
	ds_read_b128 v[192:195], v191 offset:51200
	ds_read_b128 v[198:201], v191 offset:52224
	ds_read_b128 v[204:207], v191 offset:53248
	ds_read_b128 v[208:211], v191 offset:54272
	ds_read_b128 v[212:215], v191 offset:55296
	ds_read_b128 v[216:219], v191 offset:56320
	global_load_lds_dwordx4 v[184:185], off
	s_add_i32 m0, s30, 0x2000
	s_add_u32 s30, s36, 0xb0080
	v_lshl_add_u64 v[184:185], v[220:221], 0, s[24:25]
	s_addc_u32 s31, s37, 0
	s_add_i32 s36, s58, s41
	global_load_lds_dwordx4 v[184:185], off
	v_lshl_add_u64 v[184:185], s[30:31], 0, v[154:155]
	s_mov_b32 m0, s36
	s_nop 0
	global_load_lds_dwordx4 v[184:185], off
	v_lshl_add_u64 v[184:185], s[30:31], 0, v[158:159]
	s_add_i32 m0, s36, 0x2000
	s_nop 0
	global_load_lds_dwordx4 v[184:185], off
	v_lshl_add_u64 v[184:185], v[222:223], 0, s[24:25]
	s_mov_b32 m0, s46
	s_nop 0
	global_load_lds_dwordx4 v[184:185], off
	v_lshl_add_u64 v[184:185], v[224:225], 0, s[24:25]
	s_mov_b32 m0, s47
	s_nop 0
	global_load_lds_dwordx4 v[184:185], off
	s_waitcnt vmcnt(8)
	s_waitcnt lgkmcnt(0)
	s_barrier
	s_setprio 1
	s_waitcnt lgkmcnt(0)
	v_mfma_f32_16x16x32_bf16 v[60:63], v[128:131], v[176:179], v[60:63]
	v_mfma_f32_16x16x32_bf16 v[56:59], v[136:139], v[176:179], v[56:59]
	v_mfma_f32_16x16x32_bf16 v[40:43], v[136:139], v[192:195], v[40:43]
	v_mfma_f32_16x16x32_bf16 v[44:47], v[128:131], v[192:195], v[44:47]
	v_mfma_f32_16x16x32_bf16 v[28:31], v[128:131], v[204:207], v[28:31]
	v_mfma_f32_16x16x32_bf16 v[24:27], v[136:139], v[204:207], v[24:27]
	v_mfma_f32_16x16x32_bf16 v[8:11], v[136:139], v[212:215], v[8:11]
	v_mfma_f32_16x16x32_bf16 v[12:15], v[128:131], v[212:215], v[12:15]
	v_mfma_f32_16x16x32_bf16 v[60:63], v[132:135], v[180:183], v[60:63]
	v_mfma_f32_16x16x32_bf16 v[56:59], v[140:143], v[180:183], v[56:59]
	v_mfma_f32_16x16x32_bf16 v[40:43], v[140:143], v[198:201], v[40:43]
	v_mfma_f32_16x16x32_bf16 v[44:47], v[132:135], v[198:201], v[44:47]
	v_mfma_f32_16x16x32_bf16 v[28:31], v[132:135], v[208:211], v[28:31]
	v_mfma_f32_16x16x32_bf16 v[24:27], v[140:143], v[208:211], v[24:27]
	v_mfma_f32_16x16x32_bf16 v[8:11], v[140:143], v[216:219], v[8:11]
	v_mfma_f32_16x16x32_bf16 v[12:15], v[132:135], v[216:219], v[12:15]
	s_setprio 0
	s_setprio 1
	v_mfma_f32_16x16x32_bf16 v[52:55], v[144:147], v[176:179], v[52:55]
	v_mfma_f32_16x16x32_bf16 v[48:51], v[168:171], v[176:179], v[48:51]
	v_mfma_f32_16x16x32_bf16 v[32:35], v[168:171], v[192:195], v[32:35]
	v_mfma_f32_16x16x32_bf16 v[36:39], v[144:147], v[192:195], v[36:39]
	v_mfma_f32_16x16x32_bf16 v[20:23], v[144:147], v[204:207], v[20:23]
	v_mfma_f32_16x16x32_bf16 v[16:19], v[168:171], v[204:207], v[16:19]
	v_mfma_f32_16x16x32_bf16 v[0:3], v[168:171], v[212:215], v[0:3]
	v_mfma_f32_16x16x32_bf16 v[4:7], v[144:147], v[212:215], v[4:7]
	v_mfma_f32_16x16x32_bf16 v[52:55], v[148:151], v[180:183], v[52:55]
	v_mfma_f32_16x16x32_bf16 v[48:51], v[172:175], v[180:183], v[48:51]
	v_mfma_f32_16x16x32_bf16 v[32:35], v[172:175], v[198:201], v[32:35]
	v_mfma_f32_16x16x32_bf16 v[36:39], v[148:151], v[198:201], v[36:39]
	v_mfma_f32_16x16x32_bf16 v[20:23], v[148:151], v[208:211], v[20:23]
	v_mfma_f32_16x16x32_bf16 v[16:19], v[172:175], v[208:211], v[16:19]
	v_mfma_f32_16x16x32_bf16 v[0:3], v[172:175], v[216:219], v[0:3]
	v_mfma_f32_16x16x32_bf16 v[4:7], v[148:151], v[216:219], v[4:7]
	s_setprio 0
	s_barrier
	s_add_i32 s56, s56, 2
	s_add_u32 s54, s54, 0x100
	s_addc_u32 s55, s55, 0
	s_cmp_gt_u32 s56, 41
	s_mov_b64 s[30:31], s[34:35]
	s_cbranch_scc0 .LBB0_1124
	s_and_b64 vcc, exec, s[26:27]
	s_cbranch_vccz .LBB0_1127
	s_barrier
